# peeled first K-iteration: after an epilogue its first two counted waits allow the epilogue's stores to stay in flight (vmcnt(8+S)), all four GEMM phases
# speedup vs baseline: 1.0018x; 1.0017x over previous
.LBB0_201:
	s_ashr_i32 s75, s74, 31
	s_lshl_b64 s[2:3], s[74:75], 19
	s_add_u32 s76, s60, s2
	s_addc_u32 s77, s61, s3
	s_and_b64 s[2:3], s[8:9], exec
	s_cselect_b32 s1, s77, s13
	s_cselect_b32 s2, s76, s12
	s_ashr_i32 s73, s72, 31
	s_lshl_b64 s[34:35], s[72:73], 19
	s_add_u32 s78, s36, s34
	s_addc_u32 s79, s37, s35
	s_and_b64 s[34:35], s[8:9], exec
	s_cselect_b32 s3, s79, s81
	s_cselect_b32 s34, s78, s80
	s_add_u32 s12, s12, 0x40080
	s_addc_u32 s13, s13, 0
	s_add_u32 s35, s80, 0x100
	s_addc_u32 s66, s81, 0
	s_mov_b32 s68, -2
	ds_read_b128 v[112:115], v218
	ds_read_b128 v[116:119], v218 offset:1024
	ds_read_b128 v[120:123], v218 offset:2048
	ds_read_b128 v[124:127], v218 offset:3072
	s_waitcnt vmcnt(0)
	ds_read_b128 v[128:131], v219
	ds_read_b128 v[132:135], v219 offset:1024
	ds_read_b128 v[136:139], v219 offset:2048
	ds_read_b128 v[140:143], v219 offset:3072
	s_add_u32 s69, s12, 0xfffc0080
	s_addc_u32 s73, s13, -1
	s_cmp_eq_u32 s68, 12
	s_cselect_b32 s83, s1, s73
	s_cselect_b32 s82, s2, s69
	s_cselect_b32 s81, s3, s66
	s_cselect_b32 s80, s34, s35
	v_lshl_add_u64 v[230:231], s[12:13], 0, v[192:193]
	s_add_i32 m0, s15, 0xc000
	ds_read_b128 v[152:155], v220
	ds_read_b128 v[156:159], v220 offset:1024
	ds_read_b128 v[160:163], v220 offset:2048
	ds_read_b128 v[164:167], v220 offset:3072
	ds_read_b128 v[200:203], v220 offset:4096
	ds_read_b128 v[204:207], v220 offset:5120
	ds_read_b128 v[208:211], v220 offset:6144
	ds_read_b128 v[226:229], v220 offset:7168
	global_load_lds_dwordx4 v[230:231], off
	v_lshl_add_u64 v[230:231], s[12:13], 0, v[194:195]
	s_add_i32 m0, s15, 0xe000
	s_nop 0
	global_load_lds_dwordx4 v[230:231], off
	s_cmp_eq_u32 s98, 0
	s_cbranch_scc1 .Lrx0_0n
	s_waitcnt vmcnt(16)
	s_branch .Lrx0_0j
.Lrx0_0n:
	s_waitcnt vmcnt(8)
.Lrx0_0j:
	s_waitcnt lgkmcnt(0)
	s_barrier
	s_setprio 1
	s_waitcnt lgkmcnt(0)
	v_mfma_f32_16x16x32_bf16 v[172:175], v[112:115], v[152:155], 0
	v_mfma_f32_16x16x32_bf16 v[172:175], v[116:119], v[156:159], v[172:175]
	v_mfma_f32_16x16x32_bf16 v[168:171], v[120:123], v[152:155], 0
	v_mfma_f32_16x16x32_bf16 v[168:171], v[124:127], v[156:159], v[168:171]
	v_mfma_f32_16x16x32_bf16 v[104:107], v[120:123], v[160:163], 0
	v_mfma_f32_16x16x32_bf16 v[104:107], v[124:127], v[164:167], v[104:107]
	v_mfma_f32_16x16x32_bf16 v[108:111], v[112:115], v[160:163], 0
	v_mfma_f32_16x16x32_bf16 v[108:111], v[116:119], v[164:167], v[108:111]
	v_mfma_f32_16x16x32_bf16 v[92:95], v[112:115], v[200:203], 0
	v_mfma_f32_16x16x32_bf16 v[92:95], v[116:119], v[204:207], v[92:95]
	v_mfma_f32_16x16x32_bf16 v[88:91], v[120:123], v[200:203], 0
	v_mfma_f32_16x16x32_bf16 v[88:91], v[124:127], v[204:207], v[88:91]
	v_mfma_f32_16x16x32_bf16 v[72:75], v[120:123], v[208:211], 0
	v_mfma_f32_16x16x32_bf16 v[72:75], v[124:127], v[226:229], v[72:75]
	v_mfma_f32_16x16x32_bf16 v[76:79], v[112:115], v[208:211], 0
	v_mfma_f32_16x16x32_bf16 v[76:79], v[116:119], v[226:229], v[76:79]
	s_setprio 0
	s_setprio 1
	v_mfma_f32_16x16x32_bf16 v[148:151], v[128:131], v[152:155], 0
	v_mfma_f32_16x16x32_bf16 v[148:151], v[132:135], v[156:159], v[148:151]
	v_mfma_f32_16x16x32_bf16 v[144:147], v[136:139], v[152:155], 0
	v_mfma_f32_16x16x32_bf16 v[144:147], v[140:143], v[156:159], v[144:147]
	v_mfma_f32_16x16x32_bf16 v[96:99], v[136:139], v[160:163], 0
	v_mfma_f32_16x16x32_bf16 v[96:99], v[140:143], v[164:167], v[96:99]
	v_mfma_f32_16x16x32_bf16 v[100:103], v[128:131], v[160:163], 0
	v_mfma_f32_16x16x32_bf16 v[100:103], v[132:135], v[164:167], v[100:103]
	v_mfma_f32_16x16x32_bf16 v[84:87], v[128:131], v[200:203], 0
	v_mfma_f32_16x16x32_bf16 v[84:87], v[132:135], v[204:207], v[84:87]
	v_mfma_f32_16x16x32_bf16 v[80:83], v[136:139], v[200:203], 0
	v_mfma_f32_16x16x32_bf16 v[80:83], v[140:143], v[204:207], v[80:83]
	v_mfma_f32_16x16x32_bf16 v[64:67], v[136:139], v[208:211], 0
	v_mfma_f32_16x16x32_bf16 v[64:67], v[140:143], v[226:229], v[64:67]
	v_mfma_f32_16x16x32_bf16 v[68:71], v[128:131], v[208:211], 0
	v_mfma_f32_16x16x32_bf16 v[68:71], v[132:135], v[226:229], v[68:71]
	s_setprio 0
	s_barrier
	s_add_i32 s69, s59, s14
	v_lshl_add_u64 v[230:231], s[80:81], 0, v[178:179]
	s_mov_b32 m0, s69
	ds_read_b128 v[152:155], v220 offset:16384
	ds_read_b128 v[156:159], v220 offset:17408
	ds_read_b128 v[160:163], v220 offset:18432
	ds_read_b128 v[164:167], v220 offset:19456
	ds_read_b128 v[200:203], v220 offset:20480
	ds_read_b128 v[204:207], v220 offset:21504
	ds_read_b128 v[208:211], v220 offset:22528
	ds_read_b128 v[226:229], v220 offset:23552
	global_load_lds_dwordx4 v[230:231], off
	s_add_i32 m0, s69, 0x2000
	s_add_u32 s86, s80, 0x40000
	v_lshl_add_u64 v[232:233], s[80:81], 0, v[182:183]
	s_addc_u32 s87, s81, 0
	s_add_i32 s69, s65, s14
	global_load_lds_dwordx4 v[232:233], off
	v_lshl_add_u64 v[234:235], s[86:87], 0, v[178:179]
	s_mov_b32 m0, s69
	v_lshl_add_u64 v[236:237], s[82:83], 0, v[180:181]
	global_load_lds_dwordx4 v[234:235], off
	v_lshl_add_u64 v[234:235], s[86:87], 0, v[182:183]
	s_add_i32 m0, s69, 0x2000
	s_nop 0
	global_load_lds_dwordx4 v[234:235], off
	v_lshl_add_u64 v[234:235], s[82:83], 0, v[176:177]
	s_mov_b32 m0, s15
	s_nop 0
	global_load_lds_dwordx4 v[234:235], off
	s_mov_b32 m0, s52
	s_nop 0
	global_load_lds_dwordx4 v[236:237], off
	s_cmp_eq_u32 s98, 0
	s_cbranch_scc1 .Lrx0_1n
	s_waitcnt vmcnt(16)
	s_mov_b32 s98, 0
	s_branch .Lrx0_1j

.Lrx0_1j:
	s_waitcnt lgkmcnt(0)
	s_barrier
	s_setprio 1
	s_waitcnt lgkmcnt(0)
	v_mfma_f32_16x16x32_bf16 v[60:63], v[112:115], v[152:155], 0
	v_mfma_f32_16x16x32_bf16 v[60:63], v[116:119], v[156:159], v[60:63]
	v_mfma_f32_16x16x32_bf16 v[56:59], v[120:123], v[152:155], 0
	v_mfma_f32_16x16x32_bf16 v[56:59], v[124:127], v[156:159], v[56:59]
	v_mfma_f32_16x16x32_bf16 v[40:43], v[120:123], v[160:163], 0
	v_mfma_f32_16x16x32_bf16 v[40:43], v[124:127], v[164:167], v[40:43]
	v_mfma_f32_16x16x32_bf16 v[44:47], v[112:115], v[160:163], 0
	v_mfma_f32_16x16x32_bf16 v[44:47], v[116:119], v[164:167], v[44:47]
	v_mfma_f32_16x16x32_bf16 v[28:31], v[112:115], v[200:203], 0
	v_mfma_f32_16x16x32_bf16 v[28:31], v[116:119], v[204:207], v[28:31]
	v_mfma_f32_16x16x32_bf16 v[24:27], v[120:123], v[200:203], 0
	v_mfma_f32_16x16x32_bf16 v[24:27], v[124:127], v[204:207], v[24:27]
	v_mfma_f32_16x16x32_bf16 v[8:11], v[120:123], v[208:211], 0
	v_mfma_f32_16x16x32_bf16 v[8:11], v[124:127], v[226:229], v[8:11]
	v_mfma_f32_16x16x32_bf16 v[12:15], v[112:115], v[208:211], 0
	v_mfma_f32_16x16x32_bf16 v[12:15], v[116:119], v[226:229], v[12:15]
	s_setprio 0
	s_setprio 1
	v_mfma_f32_16x16x32_bf16 v[52:55], v[128:131], v[152:155], 0
	v_mfma_f32_16x16x32_bf16 v[52:55], v[132:135], v[156:159], v[52:55]
	v_mfma_f32_16x16x32_bf16 v[48:51], v[136:139], v[152:155], 0
	v_mfma_f32_16x16x32_bf16 v[48:51], v[140:143], v[156:159], v[48:51]
	v_mfma_f32_16x16x32_bf16 v[32:35], v[136:139], v[160:163], 0
	v_mfma_f32_16x16x32_bf16 v[32:35], v[140:143], v[164:167], v[32:35]
	v_mfma_f32_16x16x32_bf16 v[36:39], v[128:131], v[160:163], 0
	v_mfma_f32_16x16x32_bf16 v[36:39], v[132:135], v[164:167], v[36:39]
	v_mfma_f32_16x16x32_bf16 v[20:23], v[128:131], v[200:203], 0
	v_mfma_f32_16x16x32_bf16 v[20:23], v[132:135], v[204:207], v[20:23]
	v_mfma_f32_16x16x32_bf16 v[16:19], v[136:139], v[200:203], 0
	v_mfma_f32_16x16x32_bf16 v[16:19], v[140:143], v[204:207], v[16:19]
	v_mfma_f32_16x16x32_bf16 v[0:3], v[136:139], v[208:211], 0
	v_mfma_f32_16x16x32_bf16 v[0:3], v[140:143], v[226:229], v[0:3]
	v_mfma_f32_16x16x32_bf16 v[4:7], v[128:131], v[208:211], 0
	v_mfma_f32_16x16x32_bf16 v[4:7], v[132:135], v[226:229], v[4:7]
	s_setprio 0
	s_barrier
	s_add_i32 s69, 0, 0x18000
	s_add_i32 s73, 0, 0x1c000
	v_add_u32_e32 v124, s69, v212
	v_add_u32_e32 v140, s73, v212
	ds_read_b128 v[112:115], v124
	ds_read_b128 v[116:119], v124 offset:1024
	ds_read_b128 v[120:123], v124 offset:2048
	ds_read_b128 v[124:127], v124 offset:3072
	ds_read_b128 v[128:131], v140
	ds_read_b128 v[132:135], v140 offset:1024
	ds_read_b128 v[136:139], v140 offset:2048
	ds_read_b128 v[140:143], v140 offset:3072
	s_add_u32 s82, s82, 0x40000
	s_addc_u32 s83, s83, 0
	s_mov_b32 m0, s53
	v_lshl_add_u64 v[238:239], s[82:83], 0, v[176:177]
	ds_read_b128 v[152:155], v220 offset:32768
	ds_read_b128 v[156:159], v220 offset:33792
	ds_read_b128 v[160:163], v220 offset:34816
	ds_read_b128 v[164:167], v220 offset:35840
	ds_read_b128 v[200:203], v220 offset:36864
	ds_read_b128 v[204:207], v220 offset:37888
	ds_read_b128 v[208:211], v220 offset:38912
	ds_read_b128 v[226:229], v220 offset:39936
	global_load_lds_dwordx4 v[238:239], off
	v_lshl_add_u64 v[238:239], s[82:83], 0, v[180:181]
	s_mov_b32 m0, s54
	s_nop 0
	global_load_lds_dwordx4 v[238:239], off
	s_waitcnt vmcnt(8)
	s_waitcnt lgkmcnt(0)
	s_barrier
	s_setprio 1
	s_waitcnt lgkmcnt(0)
	v_mfma_f32_16x16x32_bf16 v[172:175], v[112:115], v[152:155], v[172:175]
	v_mfma_f32_16x16x32_bf16 v[172:175], v[116:119], v[156:159], v[172:175]
	v_mfma_f32_16x16x32_bf16 v[168:171], v[120:123], v[152:155], v[168:171]
	v_mfma_f32_16x16x32_bf16 v[168:171], v[124:127], v[156:159], v[168:171]
	v_mfma_f32_16x16x32_bf16 v[104:107], v[120:123], v[160:163], v[104:107]
	v_mfma_f32_16x16x32_bf16 v[104:107], v[124:127], v[164:167], v[104:107]
	v_mfma_f32_16x16x32_bf16 v[108:111], v[112:115], v[160:163], v[108:111]
	v_mfma_f32_16x16x32_bf16 v[108:111], v[116:119], v[164:167], v[108:111]
	v_mfma_f32_16x16x32_bf16 v[92:95], v[112:115], v[200:203], v[92:95]
	v_mfma_f32_16x16x32_bf16 v[92:95], v[116:119], v[204:207], v[92:95]
	v_mfma_f32_16x16x32_bf16 v[88:91], v[120:123], v[200:203], v[88:91]
	v_mfma_f32_16x16x32_bf16 v[88:91], v[124:127], v[204:207], v[88:91]
	v_mfma_f32_16x16x32_bf16 v[72:75], v[120:123], v[208:211], v[72:75]
	v_mfma_f32_16x16x32_bf16 v[72:75], v[124:127], v[226:229], v[72:75]
	v_mfma_f32_16x16x32_bf16 v[76:79], v[112:115], v[208:211], v[76:79]
	v_mfma_f32_16x16x32_bf16 v[76:79], v[116:119], v[226:229], v[76:79]
	s_setprio 0
	s_setprio 1
	v_mfma_f32_16x16x32_bf16 v[148:151], v[128:131], v[152:155], v[148:151]
	v_mfma_f32_16x16x32_bf16 v[148:151], v[132:135], v[156:159], v[148:151]
	v_mfma_f32_16x16x32_bf16 v[144:147], v[136:139], v[152:155], v[144:147]
	v_mfma_f32_16x16x32_bf16 v[144:147], v[140:143], v[156:159], v[144:147]
	v_mfma_f32_16x16x32_bf16 v[96:99], v[136:139], v[160:163], v[96:99]
	v_mfma_f32_16x16x32_bf16 v[96:99], v[140:143], v[164:167], v[96:99]
	v_mfma_f32_16x16x32_bf16 v[100:103], v[128:131], v[160:163], v[100:103]
	v_mfma_f32_16x16x32_bf16 v[100:103], v[132:135], v[164:167], v[100:103]
	v_mfma_f32_16x16x32_bf16 v[84:87], v[128:131], v[200:203], v[84:87]
	v_mfma_f32_16x16x32_bf16 v[84:87], v[132:135], v[204:207], v[84:87]
	v_mfma_f32_16x16x32_bf16 v[80:83], v[136:139], v[200:203], v[80:83]
	v_mfma_f32_16x16x32_bf16 v[80:83], v[140:143], v[204:207], v[80:83]
	v_mfma_f32_16x16x32_bf16 v[64:67], v[136:139], v[208:211], v[64:67]
	v_mfma_f32_16x16x32_bf16 v[64:67], v[140:143], v[226:229], v[64:67]
	v_mfma_f32_16x16x32_bf16 v[68:71], v[128:131], v[208:211], v[68:71]
	v_mfma_f32_16x16x32_bf16 v[68:71], v[132:135], v[226:229], v[68:71]
	s_setprio 0
	s_barrier
	s_add_i32 s69, s69, s14
	v_lshl_add_u64 v[230:231], v[230:231], 0, s[40:41]
	s_mov_b32 m0, s69
	ds_read_b128 v[152:155], v220 offset:49152
	ds_read_b128 v[156:159], v220 offset:50176
	ds_read_b128 v[160:163], v220 offset:51200
	ds_read_b128 v[164:167], v220 offset:52224
	ds_read_b128 v[200:203], v220 offset:53248
	ds_read_b128 v[204:207], v220 offset:54272
	ds_read_b128 v[208:211], v220 offset:55296
	ds_read_b128 v[226:229], v220 offset:56320
	global_load_lds_dwordx4 v[230:231], off
	s_add_i32 m0, s69, 0x2000
	s_add_u32 s80, s80, 0x40080
	v_lshl_add_u64 v[230:231], v[232:233], 0, s[40:41]
	s_addc_u32 s81, s81, 0
	s_add_i32 s69, s73, s14
	global_load_lds_dwordx4 v[230:231], off
	v_lshl_add_u64 v[230:231], s[80:81], 0, v[178:179]
	s_mov_b32 m0, s69
	s_nop 0
	global_load_lds_dwordx4 v[230:231], off
	v_lshl_add_u64 v[230:231], s[80:81], 0, v[182:183]
	s_add_i32 m0, s69, 0x2000
	s_nop 0
	global_load_lds_dwordx4 v[230:231], off
	v_lshl_add_u64 v[230:231], v[234:235], 0, s[40:41]
	s_mov_b32 m0, s57
	s_nop 0
	global_load_lds_dwordx4 v[230:231], off
	v_lshl_add_u64 v[230:231], v[236:237], 0, s[40:41]
	s_mov_b32 m0, s58
	s_nop 0
	global_load_lds_dwordx4 v[230:231], off
	s_waitcnt vmcnt(8)
	s_waitcnt lgkmcnt(0)
	s_barrier
	s_setprio 1
	s_waitcnt lgkmcnt(0)
	v_mfma_f32_16x16x32_bf16 v[60:63], v[112:115], v[152:155], v[60:63]
	v_mfma_f32_16x16x32_bf16 v[60:63], v[116:119], v[156:159], v[60:63]
	v_mfma_f32_16x16x32_bf16 v[56:59], v[120:123], v[152:155], v[56:59]
	v_mfma_f32_16x16x32_bf16 v[56:59], v[124:127], v[156:159], v[56:59]
	v_mfma_f32_16x16x32_bf16 v[40:43], v[120:123], v[160:163], v[40:43]
	v_mfma_f32_16x16x32_bf16 v[40:43], v[124:127], v[164:167], v[40:43]
	v_mfma_f32_16x16x32_bf16 v[44:47], v[112:115], v[160:163], v[44:47]
	v_mfma_f32_16x16x32_bf16 v[44:47], v[116:119], v[164:167], v[44:47]
	v_mfma_f32_16x16x32_bf16 v[28:31], v[112:115], v[200:203], v[28:31]
	v_mfma_f32_16x16x32_bf16 v[28:31], v[116:119], v[204:207], v[28:31]
	v_mfma_f32_16x16x32_bf16 v[24:27], v[120:123], v[200:203], v[24:27]
	v_mfma_f32_16x16x32_bf16 v[24:27], v[124:127], v[204:207], v[24:27]
	v_mfma_f32_16x16x32_bf16 v[8:11], v[120:123], v[208:211], v[8:11]
	v_mfma_f32_16x16x32_bf16 v[8:11], v[124:127], v[226:229], v[8:11]
	v_mfma_f32_16x16x32_bf16 v[12:15], v[112:115], v[208:211], v[12:15]
	v_mfma_f32_16x16x32_bf16 v[12:15], v[116:119], v[226:229], v[12:15]
	s_setprio 0
	s_setprio 1
	v_mfma_f32_16x16x32_bf16 v[52:55], v[128:131], v[152:155], v[52:55]
	v_mfma_f32_16x16x32_bf16 v[52:55], v[132:135], v[156:159], v[52:55]
	v_mfma_f32_16x16x32_bf16 v[48:51], v[136:139], v[152:155], v[48:51]
	v_mfma_f32_16x16x32_bf16 v[48:51], v[140:143], v[156:159], v[48:51]
	v_mfma_f32_16x16x32_bf16 v[32:35], v[136:139], v[160:163], v[32:35]
	v_mfma_f32_16x16x32_bf16 v[32:35], v[140:143], v[164:167], v[32:35]
	v_mfma_f32_16x16x32_bf16 v[36:39], v[128:131], v[160:163], v[36:39]
	v_mfma_f32_16x16x32_bf16 v[36:39], v[132:135], v[164:167], v[36:39]
	v_mfma_f32_16x16x32_bf16 v[20:23], v[128:131], v[200:203], v[20:23]
	v_mfma_f32_16x16x32_bf16 v[20:23], v[132:135], v[204:207], v[20:23]
	v_mfma_f32_16x16x32_bf16 v[16:19], v[136:139], v[200:203], v[16:19]
	v_mfma_f32_16x16x32_bf16 v[16:19], v[140:143], v[204:207], v[16:19]
	v_mfma_f32_16x16x32_bf16 v[0:3], v[136:139], v[208:211], v[0:3]
	v_mfma_f32_16x16x32_bf16 v[0:3], v[140:143], v[226:229], v[0:3]
	v_mfma_f32_16x16x32_bf16 v[4:7], v[128:131], v[208:211], v[4:7]
	v_mfma_f32_16x16x32_bf16 v[4:7], v[132:135], v[226:229], v[4:7]
	s_setprio 0
	s_barrier
	s_add_i32 s68, s68, 2
	s_add_u32 s12, s12, 0x100
	s_addc_u32 s13, s13, 0
	s_add_u32 s35, s35, 0x100
	s_addc_u32 s66, s66, 0

.LBB0_253:
	s_andn2_b64 vcc, exec, s[8:9]
	s_mov_b64 s[0:1], -1
	s_mov_b32 s98, 1
	s_cbranch_vccnz .LBB0_198
	s_andn2_b64 vcc, exec, s[38:39]
	s_cbranch_vccnz .LBB0_197
	s_barrier
	s_branch .LBB0_197

.LBB0_645:
	s_ashr_i32 s31, s30, 31
	s_lshl_b64 s[36:37], s[30:31], 19
	s_add_u32 s36, s92, s36
	s_addc_u32 s37, s93, s37
	s_and_b64 s[38:39], s[8:9], exec
	s_cselect_b32 s31, s37, s43
	s_cselect_b32 s41, s36, s42
	s_ashr_i32 s29, s28, 31
	s_lshl_b64 s[38:39], s[28:29], 19
	s_add_u32 s38, s10, s38
	s_addc_u32 s39, s11, s39
	s_and_b64 s[46:47], s[8:9], exec
	s_cselect_b32 s29, s39, s45
	s_cselect_b32 s54, s38, s44
	s_add_u32 s42, s42, 0x40080
	s_addc_u32 s43, s43, 0
	s_add_u32 s55, s44, 0x100
	s_addc_u32 s56, s45, 0
	s_mov_b32 s57, -2
	s_waitcnt lgkmcnt(0)
	ds_read_b128 v[88:91], v236
	ds_read_b128 v[100:103], v236 offset:1024
	ds_read_b128 v[112:115], v236 offset:2048
	ds_read_b128 v[124:127], v236 offset:3072
	ds_read_b128 v[136:139], v237
	ds_read_b128 v[148:151], v237 offset:1024
	ds_read_b128 v[152:155], v237 offset:2048
	ds_read_b128 v[156:159], v237 offset:3072
	s_add_u32 s44, s42, 0xfffc0080
	s_addc_u32 s45, s43, -1
	s_cmp_eq_u32 s57, 12
	s_cselect_b32 s47, s31, s45
	s_cselect_b32 s46, s41, s44
	s_cselect_b32 s45, s29, s56
	s_cselect_b32 s44, s54, s55
	v_lshl_add_u64 v[208:209], s[42:43], 0, v[194:195]
	s_add_i32 m0, s3, 0xc000
	ds_read_b128 v[160:163], v238
	ds_read_b128 v[164:167], v238 offset:1024
	ds_read_b128 v[168:171], v238 offset:2048
	ds_read_b128 v[172:175], v238 offset:3072
	ds_read_b128 v[176:179], v238 offset:4096
	ds_read_b128 v[180:183], v238 offset:5120
	ds_read_b128 v[202:205], v238 offset:6144
	ds_read_b128 v[228:231], v238 offset:7168
	global_load_lds_dwordx4 v[208:209], off
	v_lshl_add_u64 v[208:209], s[42:43], 0, v[196:197]
	s_add_i32 m0, s3, 0xe000
	s_nop 0
	global_load_lds_dwordx4 v[208:209], off
	s_cmp_eq_u32 s98, 0
	s_cbranch_scc1 .Lrx1_0n
	s_waitcnt vmcnt(24)
	s_branch .Lrx1_0j

.Lrx1_0j:
	s_waitcnt lgkmcnt(0)
	s_barrier
	s_setprio 1
	s_waitcnt lgkmcnt(0)
	v_mfma_f32_16x16x32_bf16 v[144:147], v[88:91], v[160:163], 0
	v_mfma_f32_16x16x32_bf16 v[144:147], v[100:103], v[164:167], v[144:147]
	v_mfma_f32_16x16x32_bf16 v[140:143], v[112:115], v[160:163], 0
	v_mfma_f32_16x16x32_bf16 v[140:143], v[124:127], v[164:167], v[140:143]
	v_mfma_f32_16x16x32_bf16 v[116:119], v[112:115], v[168:171], 0
	v_mfma_f32_16x16x32_bf16 v[116:119], v[124:127], v[172:175], v[116:119]
	v_mfma_f32_16x16x32_bf16 v[120:123], v[88:91], v[168:171], 0
	v_mfma_f32_16x16x32_bf16 v[120:123], v[100:103], v[172:175], v[120:123]
	v_mfma_f32_16x16x32_bf16 v[96:99], v[88:91], v[176:179], 0
	v_mfma_f32_16x16x32_bf16 v[96:99], v[100:103], v[180:183], v[96:99]
	v_mfma_f32_16x16x32_bf16 v[92:95], v[112:115], v[176:179], 0
	v_mfma_f32_16x16x32_bf16 v[92:95], v[124:127], v[180:183], v[92:95]
	v_mfma_f32_16x16x32_bf16 v[72:75], v[112:115], v[202:205], 0
	v_mfma_f32_16x16x32_bf16 v[72:75], v[124:127], v[228:231], v[72:75]
	v_mfma_f32_16x16x32_bf16 v[76:79], v[88:91], v[202:205], 0
	v_mfma_f32_16x16x32_bf16 v[76:79], v[100:103], v[228:231], v[76:79]
	s_setprio 0
	s_setprio 1
	v_mfma_f32_16x16x32_bf16 v[132:135], v[136:139], v[160:163], 0
	v_mfma_f32_16x16x32_bf16 v[132:135], v[148:151], v[164:167], v[132:135]
	v_mfma_f32_16x16x32_bf16 v[128:131], v[152:155], v[160:163], 0
	v_mfma_f32_16x16x32_bf16 v[128:131], v[156:159], v[164:167], v[128:131]
	v_mfma_f32_16x16x32_bf16 v[104:107], v[152:155], v[168:171], 0
	v_mfma_f32_16x16x32_bf16 v[104:107], v[156:159], v[172:175], v[104:107]
	v_mfma_f32_16x16x32_bf16 v[108:111], v[136:139], v[168:171], 0
	v_mfma_f32_16x16x32_bf16 v[108:111], v[148:151], v[172:175], v[108:111]
	v_mfma_f32_16x16x32_bf16 v[84:87], v[136:139], v[176:179], 0
	v_mfma_f32_16x16x32_bf16 v[84:87], v[148:151], v[180:183], v[84:87]
	v_mfma_f32_16x16x32_bf16 v[80:83], v[152:155], v[176:179], 0
	v_mfma_f32_16x16x32_bf16 v[80:83], v[156:159], v[180:183], v[80:83]
	v_mfma_f32_16x16x32_bf16 v[64:67], v[152:155], v[202:205], 0
	v_mfma_f32_16x16x32_bf16 v[64:67], v[156:159], v[228:231], v[64:67]
	v_mfma_f32_16x16x32_bf16 v[68:71], v[136:139], v[202:205], 0
	v_mfma_f32_16x16x32_bf16 v[68:71], v[148:151], v[228:231], v[68:71]
	s_setprio 0
	s_barrier
	s_add_i32 s58, s51, s2
	v_lshl_add_u64 v[208:209], s[44:45], 0, v[186:187]
	s_mov_b32 m0, s58
	ds_read_b128 v[160:163], v238 offset:16384
	ds_read_b128 v[164:167], v238 offset:17408
	ds_read_b128 v[168:171], v238 offset:18432
	ds_read_b128 v[172:175], v238 offset:19456
	ds_read_b128 v[176:179], v238 offset:20480
	ds_read_b128 v[180:183], v238 offset:21504
	ds_read_b128 v[202:205], v238 offset:22528
	ds_read_b128 v[228:231], v238 offset:23552
	global_load_lds_dwordx4 v[208:209], off
	s_add_i32 m0, s58, 0x2000
	s_add_u32 s58, s44, 0x40000
	v_lshl_add_u64 v[212:213], s[44:45], 0, v[190:191]
	s_addc_u32 s59, s45, 0
	s_add_i32 s64, s52, s2
	global_load_lds_dwordx4 v[212:213], off
	v_lshl_add_u64 v[216:217], s[58:59], 0, v[186:187]
	s_mov_b32 m0, s64
	v_lshl_add_u64 v[220:221], s[46:47], 0, v[188:189]
	global_load_lds_dwordx4 v[216:217], off
	v_lshl_add_u64 v[216:217], s[58:59], 0, v[190:191]
	s_add_i32 m0, s64, 0x2000
	s_nop 0
	global_load_lds_dwordx4 v[216:217], off
	v_lshl_add_u64 v[216:217], s[46:47], 0, v[184:185]
	s_mov_b32 m0, s3
	s_nop 0
	global_load_lds_dwordx4 v[216:217], off
	s_mov_b32 m0, s33
	s_nop 0
	global_load_lds_dwordx4 v[220:221], off
	s_cmp_eq_u32 s98, 0
	s_cbranch_scc1 .Lrx1_1n
	s_waitcnt vmcnt(24)
	s_mov_b32 s98, 0
	s_branch .Lrx1_1j

.Lrx1_1j:
	s_waitcnt lgkmcnt(0)
	s_barrier
	s_setprio 1
	s_waitcnt lgkmcnt(0)
	v_mfma_f32_16x16x32_bf16 v[60:63], v[88:91], v[160:163], 0
	v_mfma_f32_16x16x32_bf16 v[60:63], v[100:103], v[164:167], v[60:63]
	v_mfma_f32_16x16x32_bf16 v[56:59], v[112:115], v[160:163], 0
	v_mfma_f32_16x16x32_bf16 v[56:59], v[124:127], v[164:167], v[56:59]
	v_mfma_f32_16x16x32_bf16 v[40:43], v[112:115], v[168:171], 0
	v_mfma_f32_16x16x32_bf16 v[40:43], v[124:127], v[172:175], v[40:43]
	v_mfma_f32_16x16x32_bf16 v[44:47], v[88:91], v[168:171], 0
	v_mfma_f32_16x16x32_bf16 v[44:47], v[100:103], v[172:175], v[44:47]
	v_mfma_f32_16x16x32_bf16 v[28:31], v[88:91], v[176:179], 0
	v_mfma_f32_16x16x32_bf16 v[28:31], v[100:103], v[180:183], v[28:31]
	v_mfma_f32_16x16x32_bf16 v[24:27], v[112:115], v[176:179], 0
	v_mfma_f32_16x16x32_bf16 v[24:27], v[124:127], v[180:183], v[24:27]
	v_mfma_f32_16x16x32_bf16 v[8:11], v[112:115], v[202:205], 0
	v_mfma_f32_16x16x32_bf16 v[8:11], v[124:127], v[228:231], v[8:11]
	v_mfma_f32_16x16x32_bf16 v[12:15], v[88:91], v[202:205], 0
	v_mfma_f32_16x16x32_bf16 v[12:15], v[100:103], v[228:231], v[12:15]
	s_setprio 0
	s_setprio 1
	v_mfma_f32_16x16x32_bf16 v[52:55], v[136:139], v[160:163], 0
	v_mfma_f32_16x16x32_bf16 v[52:55], v[148:151], v[164:167], v[52:55]
	v_mfma_f32_16x16x32_bf16 v[48:51], v[152:155], v[160:163], 0
	v_mfma_f32_16x16x32_bf16 v[48:51], v[156:159], v[164:167], v[48:51]
	v_mfma_f32_16x16x32_bf16 v[32:35], v[152:155], v[168:171], 0
	v_mfma_f32_16x16x32_bf16 v[32:35], v[156:159], v[172:175], v[32:35]
	v_mfma_f32_16x16x32_bf16 v[36:39], v[136:139], v[168:171], 0
	v_mfma_f32_16x16x32_bf16 v[36:39], v[148:151], v[172:175], v[36:39]
	v_mfma_f32_16x16x32_bf16 v[20:23], v[136:139], v[176:179], 0
	v_mfma_f32_16x16x32_bf16 v[20:23], v[148:151], v[180:183], v[20:23]
	v_mfma_f32_16x16x32_bf16 v[16:19], v[152:155], v[176:179], 0
	v_mfma_f32_16x16x32_bf16 v[16:19], v[156:159], v[180:183], v[16:19]
	v_mfma_f32_16x16x32_bf16 v[0:3], v[152:155], v[202:205], 0
	v_mfma_f32_16x16x32_bf16 v[0:3], v[156:159], v[228:231], v[0:3]
	v_mfma_f32_16x16x32_bf16 v[4:7], v[136:139], v[202:205], 0
	v_mfma_f32_16x16x32_bf16 v[4:7], v[148:151], v[228:231], v[4:7]
	s_setprio 0
	s_barrier
	s_add_i32 s58, 0, 0x18000
	s_add_i32 s59, 0, 0x1c000
	v_add_u32_e32 v124, s58, v211
	v_add_u32_e32 v156, s59, v211
	ds_read_b128 v[88:91], v124
	ds_read_b128 v[100:103], v124 offset:1024
	ds_read_b128 v[112:115], v124 offset:2048
	ds_read_b128 v[124:127], v124 offset:3072
	ds_read_b128 v[136:139], v156
	ds_read_b128 v[148:151], v156 offset:1024
	ds_read_b128 v[152:155], v156 offset:2048
	ds_read_b128 v[156:159], v156 offset:3072
	s_add_u32 s46, s46, 0x40000
	s_addc_u32 s47, s47, 0
	s_mov_b32 m0, s34
	v_lshl_add_u64 v[224:225], s[46:47], 0, v[184:185]
	ds_read_b128 v[160:163], v238 offset:32768
	ds_read_b128 v[164:167], v238 offset:33792
	ds_read_b128 v[168:171], v238 offset:34816
	ds_read_b128 v[172:175], v238 offset:35840
	ds_read_b128 v[176:179], v238 offset:36864
	ds_read_b128 v[180:183], v238 offset:37888
	ds_read_b128 v[202:205], v238 offset:38912
	ds_read_b128 v[228:231], v238 offset:39936
	global_load_lds_dwordx4 v[224:225], off
	v_lshl_add_u64 v[224:225], s[46:47], 0, v[188:189]
	s_mov_b32 m0, s35
	s_nop 0
	global_load_lds_dwordx4 v[224:225], off
	s_waitcnt vmcnt(8)
	s_waitcnt lgkmcnt(0)
	s_barrier
	s_setprio 1
	s_waitcnt lgkmcnt(0)
	v_mfma_f32_16x16x32_bf16 v[144:147], v[88:91], v[160:163], v[144:147]
	v_mfma_f32_16x16x32_bf16 v[144:147], v[100:103], v[164:167], v[144:147]
	v_mfma_f32_16x16x32_bf16 v[140:143], v[112:115], v[160:163], v[140:143]
	v_mfma_f32_16x16x32_bf16 v[140:143], v[124:127], v[164:167], v[140:143]
	v_mfma_f32_16x16x32_bf16 v[116:119], v[112:115], v[168:171], v[116:119]
	v_mfma_f32_16x16x32_bf16 v[116:119], v[124:127], v[172:175], v[116:119]
	v_mfma_f32_16x16x32_bf16 v[120:123], v[88:91], v[168:171], v[120:123]
	v_mfma_f32_16x16x32_bf16 v[120:123], v[100:103], v[172:175], v[120:123]
	v_mfma_f32_16x16x32_bf16 v[96:99], v[88:91], v[176:179], v[96:99]
	v_mfma_f32_16x16x32_bf16 v[96:99], v[100:103], v[180:183], v[96:99]
	v_mfma_f32_16x16x32_bf16 v[92:95], v[112:115], v[176:179], v[92:95]
	v_mfma_f32_16x16x32_bf16 v[92:95], v[124:127], v[180:183], v[92:95]
	v_mfma_f32_16x16x32_bf16 v[72:75], v[112:115], v[202:205], v[72:75]
	v_mfma_f32_16x16x32_bf16 v[72:75], v[124:127], v[228:231], v[72:75]
	v_mfma_f32_16x16x32_bf16 v[76:79], v[88:91], v[202:205], v[76:79]
	v_mfma_f32_16x16x32_bf16 v[76:79], v[100:103], v[228:231], v[76:79]
	s_setprio 0
	s_setprio 1
	v_mfma_f32_16x16x32_bf16 v[132:135], v[136:139], v[160:163], v[132:135]
	v_mfma_f32_16x16x32_bf16 v[132:135], v[148:151], v[164:167], v[132:135]
	v_mfma_f32_16x16x32_bf16 v[128:131], v[152:155], v[160:163], v[128:131]
	v_mfma_f32_16x16x32_bf16 v[128:131], v[156:159], v[164:167], v[128:131]
	v_mfma_f32_16x16x32_bf16 v[104:107], v[152:155], v[168:171], v[104:107]
	v_mfma_f32_16x16x32_bf16 v[104:107], v[156:159], v[172:175], v[104:107]
	v_mfma_f32_16x16x32_bf16 v[108:111], v[136:139], v[168:171], v[108:111]
	v_mfma_f32_16x16x32_bf16 v[108:111], v[148:151], v[172:175], v[108:111]
	v_mfma_f32_16x16x32_bf16 v[84:87], v[136:139], v[176:179], v[84:87]
	v_mfma_f32_16x16x32_bf16 v[84:87], v[148:151], v[180:183], v[84:87]
	v_mfma_f32_16x16x32_bf16 v[80:83], v[152:155], v[176:179], v[80:83]
	v_mfma_f32_16x16x32_bf16 v[80:83], v[156:159], v[180:183], v[80:83]
	v_mfma_f32_16x16x32_bf16 v[64:67], v[152:155], v[202:205], v[64:67]
	v_mfma_f32_16x16x32_bf16 v[64:67], v[156:159], v[228:231], v[64:67]
	v_mfma_f32_16x16x32_bf16 v[68:71], v[136:139], v[202:205], v[68:71]
	v_mfma_f32_16x16x32_bf16 v[68:71], v[148:151], v[228:231], v[68:71]
	s_setprio 0
	s_barrier
	s_add_i32 s46, s58, s2
	v_lshl_add_u64 v[208:209], v[208:209], 0, s[24:25]
	s_mov_b32 m0, s46
	ds_read_b128 v[160:163], v238 offset:49152
	ds_read_b128 v[164:167], v238 offset:50176
	ds_read_b128 v[168:171], v238 offset:51200
	ds_read_b128 v[172:175], v238 offset:52224
	ds_read_b128 v[176:179], v238 offset:53248
	ds_read_b128 v[180:183], v238 offset:54272
	ds_read_b128 v[202:205], v238 offset:55296
	ds_read_b128 v[228:231], v238 offset:56320
	global_load_lds_dwordx4 v[208:209], off
	s_add_i32 m0, s46, 0x2000
	s_add_u32 s44, s44, 0x40080
	v_lshl_add_u64 v[208:209], v[212:213], 0, s[24:25]
	s_addc_u32 s45, s45, 0
	s_add_i32 s46, s59, s2
	global_load_lds_dwordx4 v[208:209], off
	v_lshl_add_u64 v[208:209], s[44:45], 0, v[186:187]
	s_mov_b32 m0, s46
	s_nop 0
	global_load_lds_dwordx4 v[208:209], off
	v_lshl_add_u64 v[208:209], s[44:45], 0, v[190:191]
	s_add_i32 m0, s46, 0x2000
	s_nop 0
	global_load_lds_dwordx4 v[208:209], off
	v_lshl_add_u64 v[208:209], v[216:217], 0, s[24:25]
	s_mov_b32 m0, s49
	s_nop 0
	global_load_lds_dwordx4 v[208:209], off
	v_lshl_add_u64 v[208:209], v[220:221], 0, s[24:25]
	s_mov_b32 m0, s50
	s_nop 0
	global_load_lds_dwordx4 v[208:209], off
	s_waitcnt vmcnt(8)
	s_waitcnt lgkmcnt(0)
	s_barrier
	s_setprio 1
	s_waitcnt lgkmcnt(0)
	v_mfma_f32_16x16x32_bf16 v[60:63], v[88:91], v[160:163], v[60:63]
	v_mfma_f32_16x16x32_bf16 v[60:63], v[100:103], v[164:167], v[60:63]
	v_mfma_f32_16x16x32_bf16 v[56:59], v[112:115], v[160:163], v[56:59]
	v_mfma_f32_16x16x32_bf16 v[56:59], v[124:127], v[164:167], v[56:59]
	v_mfma_f32_16x16x32_bf16 v[40:43], v[112:115], v[168:171], v[40:43]
	v_mfma_f32_16x16x32_bf16 v[40:43], v[124:127], v[172:175], v[40:43]
	v_mfma_f32_16x16x32_bf16 v[44:47], v[88:91], v[168:171], v[44:47]
	v_mfma_f32_16x16x32_bf16 v[44:47], v[100:103], v[172:175], v[44:47]
	v_mfma_f32_16x16x32_bf16 v[28:31], v[88:91], v[176:179], v[28:31]
	v_mfma_f32_16x16x32_bf16 v[28:31], v[100:103], v[180:183], v[28:31]
	v_mfma_f32_16x16x32_bf16 v[24:27], v[112:115], v[176:179], v[24:27]
	v_mfma_f32_16x16x32_bf16 v[24:27], v[124:127], v[180:183], v[24:27]
	v_mfma_f32_16x16x32_bf16 v[8:11], v[112:115], v[202:205], v[8:11]
	v_mfma_f32_16x16x32_bf16 v[8:11], v[124:127], v[228:231], v[8:11]
	v_mfma_f32_16x16x32_bf16 v[12:15], v[88:91], v[202:205], v[12:15]
	v_mfma_f32_16x16x32_bf16 v[12:15], v[100:103], v[228:231], v[12:15]
	s_setprio 0
	s_setprio 1
	v_mfma_f32_16x16x32_bf16 v[52:55], v[136:139], v[160:163], v[52:55]
	v_mfma_f32_16x16x32_bf16 v[52:55], v[148:151], v[164:167], v[52:55]
	v_mfma_f32_16x16x32_bf16 v[48:51], v[152:155], v[160:163], v[48:51]
	v_mfma_f32_16x16x32_bf16 v[48:51], v[156:159], v[164:167], v[48:51]
	v_mfma_f32_16x16x32_bf16 v[32:35], v[152:155], v[168:171], v[32:35]
	v_mfma_f32_16x16x32_bf16 v[32:35], v[156:159], v[172:175], v[32:35]
	v_mfma_f32_16x16x32_bf16 v[36:39], v[136:139], v[168:171], v[36:39]
	v_mfma_f32_16x16x32_bf16 v[36:39], v[148:151], v[172:175], v[36:39]
	v_mfma_f32_16x16x32_bf16 v[20:23], v[136:139], v[176:179], v[20:23]
	v_mfma_f32_16x16x32_bf16 v[20:23], v[148:151], v[180:183], v[20:23]
	v_mfma_f32_16x16x32_bf16 v[16:19], v[152:155], v[176:179], v[16:19]
	v_mfma_f32_16x16x32_bf16 v[16:19], v[156:159], v[180:183], v[16:19]
	v_mfma_f32_16x16x32_bf16 v[0:3], v[152:155], v[202:205], v[0:3]
	v_mfma_f32_16x16x32_bf16 v[0:3], v[156:159], v[228:231], v[0:3]
	v_mfma_f32_16x16x32_bf16 v[4:7], v[136:139], v[202:205], v[4:7]
	v_mfma_f32_16x16x32_bf16 v[4:7], v[148:151], v[228:231], v[4:7]
	s_setprio 0
	s_barrier
	s_add_i32 s57, s57, 2
	s_add_u32 s42, s42, 0x100
	s_addc_u32 s43, s43, 0
	s_add_u32 s55, s55, 0x100
	s_addc_u32 s56, s56, 0

.LBB0_665:
	s_or_b64 exec, exec, s[42:43]
	s_andn2_b64 vcc, exec, s[8:9]
	s_mov_b64 s[8:9], -1
	s_mov_b32 s98, 1
	s_cbranch_vccnz .LBB0_638
	s_andn2_b64 vcc, exec, s[22:23]
	s_cbranch_vccnz .LBB0_637
	s_barrier
	s_branch .LBB0_637

.LBB0_750:
	s_ashr_i32 s25, s24, 31
	s_lshl_b64 s[26:27], s[24:25], 19
	s_add_u32 s26, s14, s26
	s_addc_u32 s27, s15, s27
	s_and_b64 s[28:29], s[6:7], exec
	s_cselect_b32 s25, s27, s37
	s_cselect_b32 s50, s26, s36
	s_ashr_i32 s23, s22, 31
	s_lshl_b64 s[28:29], s[22:23], 19
	s_add_u32 s28, s16, s28
	s_addc_u32 s29, s17, s29
	s_and_b64 s[40:41], s[6:7], exec
	s_cselect_b32 s23, s29, s39
	s_cselect_b32 s51, s28, s38
	s_add_u32 s36, s36, 0x40080
	s_addc_u32 s37, s37, 0
	s_add_u32 s52, s38, 0x100
	s_addc_u32 s53, s39, 0
	s_mov_b32 s54, -2
	ds_read_b128 v[156:159], v152
	ds_read_b128 v[160:163], v152 offset:1024
	ds_read_b128 v[164:167], v152 offset:2048
	ds_read_b128 v[168:171], v152 offset:3072
	ds_read_b128 v[172:175], v153
	ds_read_b128 v[176:179], v153 offset:1024
	ds_read_b128 v[180:183], v153 offset:2048
	ds_read_b128 v[184:187], v153 offset:3072
	s_add_u32 s38, s36, 0xfffc0080
	s_addc_u32 s39, s37, -1
	s_cmp_eq_u32 s54, 12
	s_cselect_b32 s41, s25, s39
	s_cselect_b32 s40, s50, s38
	s_cselect_b32 s39, s23, s53
	s_cselect_b32 s38, s51, s52
	v_lshl_add_u64 v[146:147], s[36:37], 0, v[138:139]
	s_add_i32 m0, s31, 0xc000
	ds_read_b128 v[188:191], v154
	ds_read_b128 v[192:195], v154 offset:1024
	ds_read_b128 v[196:199], v154 offset:2048
	ds_read_b128 v[200:203], v154 offset:3072
	ds_read_b128 v[204:207], v154 offset:4096
	ds_read_b128 v[208:211], v154 offset:5120
	ds_read_b128 v[216:219], v154 offset:6144
	ds_read_b128 v[220:223], v154 offset:7168
	global_load_lds_dwordx4 v[146:147], off
	v_lshl_add_u64 v[146:147], s[36:37], 0, v[140:141]
	s_add_i32 m0, s31, 0xe000
	s_nop 0
	global_load_lds_dwordx4 v[146:147], off
	s_cmp_eq_u32 s98, 0
	s_cbranch_scc1 .Lrx2_0n
	s_waitcnt vmcnt(24)
	s_branch .Lrx2_0j

.Lrx2_0j:
	s_waitcnt lgkmcnt(0)
	s_barrier
	s_setprio 1
	s_waitcnt lgkmcnt(0)
	v_mfma_f32_16x16x32_bf16 v[124:127], v[156:159], v[188:191], 0
	v_mfma_f32_16x16x32_bf16 v[124:127], v[160:163], v[192:195], v[124:127]
	v_mfma_f32_16x16x32_bf16 v[120:123], v[164:167], v[188:191], 0
	v_mfma_f32_16x16x32_bf16 v[120:123], v[168:171], v[192:195], v[120:123]
	v_mfma_f32_16x16x32_bf16 v[104:107], v[164:167], v[196:199], 0
	v_mfma_f32_16x16x32_bf16 v[104:107], v[168:171], v[200:203], v[104:107]
	v_mfma_f32_16x16x32_bf16 v[108:111], v[156:159], v[196:199], 0
	v_mfma_f32_16x16x32_bf16 v[108:111], v[160:163], v[200:203], v[108:111]
	v_mfma_f32_16x16x32_bf16 v[92:95], v[156:159], v[204:207], 0
	v_mfma_f32_16x16x32_bf16 v[92:95], v[160:163], v[208:211], v[92:95]
	v_mfma_f32_16x16x32_bf16 v[88:91], v[164:167], v[204:207], 0
	v_mfma_f32_16x16x32_bf16 v[88:91], v[168:171], v[208:211], v[88:91]
	v_mfma_f32_16x16x32_bf16 v[72:75], v[164:167], v[216:219], 0
	v_mfma_f32_16x16x32_bf16 v[72:75], v[168:171], v[220:223], v[72:75]
	v_mfma_f32_16x16x32_bf16 v[76:79], v[156:159], v[216:219], 0
	v_mfma_f32_16x16x32_bf16 v[76:79], v[160:163], v[220:223], v[76:79]
	s_setprio 0
	s_setprio 1
	v_mfma_f32_16x16x32_bf16 v[116:119], v[172:175], v[188:191], 0
	v_mfma_f32_16x16x32_bf16 v[116:119], v[176:179], v[192:195], v[116:119]
	v_mfma_f32_16x16x32_bf16 v[112:115], v[180:183], v[188:191], 0
	v_mfma_f32_16x16x32_bf16 v[112:115], v[184:187], v[192:195], v[112:115]
	v_mfma_f32_16x16x32_bf16 v[96:99], v[180:183], v[196:199], 0
	v_mfma_f32_16x16x32_bf16 v[96:99], v[184:187], v[200:203], v[96:99]
	v_mfma_f32_16x16x32_bf16 v[100:103], v[172:175], v[196:199], 0
	v_mfma_f32_16x16x32_bf16 v[100:103], v[176:179], v[200:203], v[100:103]
	v_mfma_f32_16x16x32_bf16 v[84:87], v[172:175], v[204:207], 0
	v_mfma_f32_16x16x32_bf16 v[84:87], v[176:179], v[208:211], v[84:87]
	v_mfma_f32_16x16x32_bf16 v[80:83], v[180:183], v[204:207], 0
	v_mfma_f32_16x16x32_bf16 v[80:83], v[184:187], v[208:211], v[80:83]
	v_mfma_f32_16x16x32_bf16 v[64:67], v[180:183], v[216:219], 0
	v_mfma_f32_16x16x32_bf16 v[64:67], v[184:187], v[220:223], v[64:67]
	v_mfma_f32_16x16x32_bf16 v[68:71], v[172:175], v[216:219], 0
	v_mfma_f32_16x16x32_bf16 v[68:71], v[176:179], v[220:223], v[68:71]
	s_setprio 0
	s_barrier
	s_add_i32 s55, s47, s33
	v_lshl_add_u64 v[146:147], s[38:39], 0, v[132:133]
	s_mov_b32 m0, s55
	ds_read_b128 v[188:191], v154 offset:16384
	ds_read_b128 v[192:195], v154 offset:17408
	ds_read_b128 v[196:199], v154 offset:18432
	ds_read_b128 v[200:203], v154 offset:19456
	ds_read_b128 v[204:207], v154 offset:20480
	ds_read_b128 v[208:211], v154 offset:21504
	ds_read_b128 v[216:219], v154 offset:22528
	ds_read_b128 v[220:223], v154 offset:23552
	global_load_lds_dwordx4 v[146:147], off
	s_add_i32 m0, s55, 0x2000
	s_add_u32 s56, s38, 0x40000
	v_lshl_add_u64 v[212:213], s[38:39], 0, v[128:129]
	s_addc_u32 s57, s39, 0
	s_add_i32 s55, s48, s33
	global_load_lds_dwordx4 v[212:213], off
	v_lshl_add_u64 v[224:225], s[56:57], 0, v[132:133]
	s_mov_b32 m0, s55
	v_lshl_add_u64 v[226:227], s[40:41], 0, v[130:131]
	global_load_lds_dwordx4 v[224:225], off
	v_lshl_add_u64 v[224:225], s[56:57], 0, v[128:129]
	s_add_i32 m0, s55, 0x2000
	s_nop 0
	global_load_lds_dwordx4 v[224:225], off
	v_lshl_add_u64 v[224:225], s[40:41], 0, v[134:135]
	s_mov_b32 m0, s31
	s_nop 0
	global_load_lds_dwordx4 v[224:225], off
	s_mov_b32 m0, s34
	s_nop 0
	global_load_lds_dwordx4 v[226:227], off
	s_cmp_eq_u32 s98, 0
	s_cbranch_scc1 .Lrx2_1n
	s_waitcnt vmcnt(24)
	s_mov_b32 s98, 0
	s_branch .Lrx2_1j

.Lrx2_1j:
	s_waitcnt lgkmcnt(0)
	s_barrier
	s_setprio 1
	s_waitcnt lgkmcnt(0)
	v_mfma_f32_16x16x32_bf16 v[60:63], v[156:159], v[188:191], 0
	v_mfma_f32_16x16x32_bf16 v[60:63], v[160:163], v[192:195], v[60:63]
	v_mfma_f32_16x16x32_bf16 v[56:59], v[164:167], v[188:191], 0
	v_mfma_f32_16x16x32_bf16 v[56:59], v[168:171], v[192:195], v[56:59]
	v_mfma_f32_16x16x32_bf16 v[40:43], v[164:167], v[196:199], 0
	v_mfma_f32_16x16x32_bf16 v[40:43], v[168:171], v[200:203], v[40:43]
	v_mfma_f32_16x16x32_bf16 v[44:47], v[156:159], v[196:199], 0
	v_mfma_f32_16x16x32_bf16 v[44:47], v[160:163], v[200:203], v[44:47]
	v_mfma_f32_16x16x32_bf16 v[28:31], v[156:159], v[204:207], 0
	v_mfma_f32_16x16x32_bf16 v[28:31], v[160:163], v[208:211], v[28:31]
	v_mfma_f32_16x16x32_bf16 v[24:27], v[164:167], v[204:207], 0
	v_mfma_f32_16x16x32_bf16 v[24:27], v[168:171], v[208:211], v[24:27]
	v_mfma_f32_16x16x32_bf16 v[8:11], v[164:167], v[216:219], 0
	v_mfma_f32_16x16x32_bf16 v[8:11], v[168:171], v[220:223], v[8:11]
	v_mfma_f32_16x16x32_bf16 v[12:15], v[156:159], v[216:219], 0
	v_mfma_f32_16x16x32_bf16 v[12:15], v[160:163], v[220:223], v[12:15]
	s_setprio 0
	s_setprio 1
	v_mfma_f32_16x16x32_bf16 v[52:55], v[172:175], v[188:191], 0
	v_mfma_f32_16x16x32_bf16 v[52:55], v[176:179], v[192:195], v[52:55]
	v_mfma_f32_16x16x32_bf16 v[48:51], v[180:183], v[188:191], 0
	v_mfma_f32_16x16x32_bf16 v[48:51], v[184:187], v[192:195], v[48:51]
	v_mfma_f32_16x16x32_bf16 v[32:35], v[180:183], v[196:199], 0
	v_mfma_f32_16x16x32_bf16 v[32:35], v[184:187], v[200:203], v[32:35]
	v_mfma_f32_16x16x32_bf16 v[36:39], v[172:175], v[196:199], 0
	v_mfma_f32_16x16x32_bf16 v[36:39], v[176:179], v[200:203], v[36:39]
	v_mfma_f32_16x16x32_bf16 v[20:23], v[172:175], v[204:207], 0
	v_mfma_f32_16x16x32_bf16 v[20:23], v[176:179], v[208:211], v[20:23]
	v_mfma_f32_16x16x32_bf16 v[16:19], v[180:183], v[204:207], 0
	v_mfma_f32_16x16x32_bf16 v[16:19], v[184:187], v[208:211], v[16:19]
	v_mfma_f32_16x16x32_bf16 v[0:3], v[180:183], v[216:219], 0
	v_mfma_f32_16x16x32_bf16 v[0:3], v[184:187], v[220:223], v[0:3]
	v_mfma_f32_16x16x32_bf16 v[4:7], v[172:175], v[216:219], 0
	v_mfma_f32_16x16x32_bf16 v[4:7], v[176:179], v[220:223], v[4:7]
	s_setprio 0
	s_barrier
	s_add_i32 s55, 0, 0x18000
	v_add_u32_e32 v155, s55, v148
	s_add_i32 s56, 0, 0x1c000
	ds_read_b128 v[156:159], v155
	ds_read_b128 v[160:163], v155 offset:1024
	ds_read_b128 v[164:167], v155 offset:2048
	ds_read_b128 v[168:171], v155 offset:3072
	v_add_u32_e32 v155, s56, v148
	ds_read_b128 v[172:175], v155
	ds_read_b128 v[176:179], v155 offset:1024
	ds_read_b128 v[180:183], v155 offset:2048
	ds_read_b128 v[184:187], v155 offset:3072
	s_add_u32 s40, s40, 0x40000
	s_addc_u32 s41, s41, 0
	s_mov_b32 m0, s35
	v_lshl_add_u64 v[228:229], s[40:41], 0, v[134:135]
	ds_read_b128 v[188:191], v154 offset:32768
	ds_read_b128 v[192:195], v154 offset:33792
	ds_read_b128 v[196:199], v154 offset:34816
	ds_read_b128 v[200:203], v154 offset:35840
	ds_read_b128 v[204:207], v154 offset:36864
	ds_read_b128 v[208:211], v154 offset:37888
	ds_read_b128 v[216:219], v154 offset:38912
	ds_read_b128 v[220:223], v154 offset:39936
	global_load_lds_dwordx4 v[228:229], off
	v_lshl_add_u64 v[228:229], s[40:41], 0, v[130:131]
	s_mov_b32 m0, s42
	s_nop 0
	global_load_lds_dwordx4 v[228:229], off
	s_waitcnt vmcnt(8)
	s_waitcnt lgkmcnt(0)
	s_barrier
	s_setprio 1
	s_waitcnt lgkmcnt(0)
	v_mfma_f32_16x16x32_bf16 v[124:127], v[156:159], v[188:191], v[124:127]
	v_mfma_f32_16x16x32_bf16 v[124:127], v[160:163], v[192:195], v[124:127]
	v_mfma_f32_16x16x32_bf16 v[120:123], v[164:167], v[188:191], v[120:123]
	v_mfma_f32_16x16x32_bf16 v[120:123], v[168:171], v[192:195], v[120:123]
	v_mfma_f32_16x16x32_bf16 v[104:107], v[164:167], v[196:199], v[104:107]
	v_mfma_f32_16x16x32_bf16 v[104:107], v[168:171], v[200:203], v[104:107]
	v_mfma_f32_16x16x32_bf16 v[108:111], v[156:159], v[196:199], v[108:111]
	v_mfma_f32_16x16x32_bf16 v[108:111], v[160:163], v[200:203], v[108:111]
	v_mfma_f32_16x16x32_bf16 v[92:95], v[156:159], v[204:207], v[92:95]
	v_mfma_f32_16x16x32_bf16 v[92:95], v[160:163], v[208:211], v[92:95]
	v_mfma_f32_16x16x32_bf16 v[88:91], v[164:167], v[204:207], v[88:91]
	v_mfma_f32_16x16x32_bf16 v[88:91], v[168:171], v[208:211], v[88:91]
	v_mfma_f32_16x16x32_bf16 v[72:75], v[164:167], v[216:219], v[72:75]
	v_mfma_f32_16x16x32_bf16 v[72:75], v[168:171], v[220:223], v[72:75]
	v_mfma_f32_16x16x32_bf16 v[76:79], v[156:159], v[216:219], v[76:79]
	v_mfma_f32_16x16x32_bf16 v[76:79], v[160:163], v[220:223], v[76:79]
	s_setprio 0
	s_setprio 1
	v_mfma_f32_16x16x32_bf16 v[116:119], v[172:175], v[188:191], v[116:119]
	v_mfma_f32_16x16x32_bf16 v[116:119], v[176:179], v[192:195], v[116:119]
	v_mfma_f32_16x16x32_bf16 v[112:115], v[180:183], v[188:191], v[112:115]
	v_mfma_f32_16x16x32_bf16 v[112:115], v[184:187], v[192:195], v[112:115]
	v_mfma_f32_16x16x32_bf16 v[96:99], v[180:183], v[196:199], v[96:99]
	v_mfma_f32_16x16x32_bf16 v[96:99], v[184:187], v[200:203], v[96:99]
	v_mfma_f32_16x16x32_bf16 v[100:103], v[172:175], v[196:199], v[100:103]
	v_mfma_f32_16x16x32_bf16 v[100:103], v[176:179], v[200:203], v[100:103]
	v_mfma_f32_16x16x32_bf16 v[84:87], v[172:175], v[204:207], v[84:87]
	v_mfma_f32_16x16x32_bf16 v[84:87], v[176:179], v[208:211], v[84:87]
	v_mfma_f32_16x16x32_bf16 v[80:83], v[180:183], v[204:207], v[80:83]
	v_mfma_f32_16x16x32_bf16 v[80:83], v[184:187], v[208:211], v[80:83]
	v_mfma_f32_16x16x32_bf16 v[64:67], v[180:183], v[216:219], v[64:67]
	v_mfma_f32_16x16x32_bf16 v[64:67], v[184:187], v[220:223], v[64:67]
	v_mfma_f32_16x16x32_bf16 v[68:71], v[172:175], v[216:219], v[68:71]
	v_mfma_f32_16x16x32_bf16 v[68:71], v[176:179], v[220:223], v[68:71]
	s_setprio 0
	s_barrier
	s_add_i32 s40, s55, s33
	v_lshl_add_u64 v[146:147], v[146:147], 0, s[18:19]
	s_mov_b32 m0, s40
	ds_read_b128 v[188:191], v154 offset:49152
	ds_read_b128 v[192:195], v154 offset:50176
	ds_read_b128 v[196:199], v154 offset:51200
	ds_read_b128 v[200:203], v154 offset:52224
	ds_read_b128 v[204:207], v154 offset:53248
	ds_read_b128 v[208:211], v154 offset:54272
	ds_read_b128 v[216:219], v154 offset:55296
	ds_read_b128 v[220:223], v154 offset:56320
	global_load_lds_dwordx4 v[146:147], off
	s_add_i32 m0, s40, 0x2000
	s_add_u32 s38, s38, 0x40080
	v_lshl_add_u64 v[146:147], v[212:213], 0, s[18:19]
	s_addc_u32 s39, s39, 0
	s_add_i32 s40, s56, s33
	global_load_lds_dwordx4 v[146:147], off
	v_lshl_add_u64 v[146:147], s[38:39], 0, v[132:133]
	s_mov_b32 m0, s40
	s_nop 0
	global_load_lds_dwordx4 v[146:147], off
	v_lshl_add_u64 v[146:147], s[38:39], 0, v[128:129]
	s_add_i32 m0, s40, 0x2000
	s_nop 0
	global_load_lds_dwordx4 v[146:147], off
	v_lshl_add_u64 v[146:147], v[224:225], 0, s[18:19]
	s_mov_b32 m0, s44
	s_nop 0
	global_load_lds_dwordx4 v[146:147], off
	v_lshl_add_u64 v[146:147], v[226:227], 0, s[18:19]
	s_mov_b32 m0, s45
	s_nop 0
	global_load_lds_dwordx4 v[146:147], off
	s_waitcnt vmcnt(8)
	s_waitcnt lgkmcnt(0)
	s_barrier
	s_setprio 1
	s_waitcnt lgkmcnt(0)
	v_mfma_f32_16x16x32_bf16 v[60:63], v[156:159], v[188:191], v[60:63]
	v_mfma_f32_16x16x32_bf16 v[60:63], v[160:163], v[192:195], v[60:63]
	v_mfma_f32_16x16x32_bf16 v[56:59], v[164:167], v[188:191], v[56:59]
	v_mfma_f32_16x16x32_bf16 v[56:59], v[168:171], v[192:195], v[56:59]
	v_mfma_f32_16x16x32_bf16 v[40:43], v[164:167], v[196:199], v[40:43]
	v_mfma_f32_16x16x32_bf16 v[40:43], v[168:171], v[200:203], v[40:43]
	v_mfma_f32_16x16x32_bf16 v[44:47], v[156:159], v[196:199], v[44:47]
	v_mfma_f32_16x16x32_bf16 v[44:47], v[160:163], v[200:203], v[44:47]
	v_mfma_f32_16x16x32_bf16 v[28:31], v[156:159], v[204:207], v[28:31]
	v_mfma_f32_16x16x32_bf16 v[28:31], v[160:163], v[208:211], v[28:31]
	v_mfma_f32_16x16x32_bf16 v[24:27], v[164:167], v[204:207], v[24:27]
	v_mfma_f32_16x16x32_bf16 v[24:27], v[168:171], v[208:211], v[24:27]
	v_mfma_f32_16x16x32_bf16 v[8:11], v[164:167], v[216:219], v[8:11]
	v_mfma_f32_16x16x32_bf16 v[8:11], v[168:171], v[220:223], v[8:11]
	v_mfma_f32_16x16x32_bf16 v[12:15], v[156:159], v[216:219], v[12:15]
	v_mfma_f32_16x16x32_bf16 v[12:15], v[160:163], v[220:223], v[12:15]
	s_setprio 0
	s_setprio 1
	v_mfma_f32_16x16x32_bf16 v[52:55], v[172:175], v[188:191], v[52:55]
	v_mfma_f32_16x16x32_bf16 v[52:55], v[176:179], v[192:195], v[52:55]
	v_mfma_f32_16x16x32_bf16 v[48:51], v[180:183], v[188:191], v[48:51]
	v_mfma_f32_16x16x32_bf16 v[48:51], v[184:187], v[192:195], v[48:51]
	v_mfma_f32_16x16x32_bf16 v[32:35], v[180:183], v[196:199], v[32:35]
	v_mfma_f32_16x16x32_bf16 v[32:35], v[184:187], v[200:203], v[32:35]
	v_mfma_f32_16x16x32_bf16 v[36:39], v[172:175], v[196:199], v[36:39]
	v_mfma_f32_16x16x32_bf16 v[36:39], v[176:179], v[200:203], v[36:39]
	v_mfma_f32_16x16x32_bf16 v[20:23], v[172:175], v[204:207], v[20:23]
	v_mfma_f32_16x16x32_bf16 v[20:23], v[176:179], v[208:211], v[20:23]
	v_mfma_f32_16x16x32_bf16 v[16:19], v[180:183], v[204:207], v[16:19]
	v_mfma_f32_16x16x32_bf16 v[16:19], v[184:187], v[208:211], v[16:19]
	v_mfma_f32_16x16x32_bf16 v[0:3], v[180:183], v[216:219], v[0:3]
	v_mfma_f32_16x16x32_bf16 v[0:3], v[184:187], v[220:223], v[0:3]
	v_mfma_f32_16x16x32_bf16 v[4:7], v[172:175], v[216:219], v[4:7]
	v_mfma_f32_16x16x32_bf16 v[4:7], v[176:179], v[220:223], v[4:7]
	s_setprio 0
	s_barrier
	s_add_i32 s54, s54, 2
	s_add_u32 s36, s36, 0x100
	s_addc_u32 s37, s37, 0
	s_add_u32 s52, s52, 0x100
	s_addc_u32 s53, s53, 0

.LBB0_754:
	s_lshl_b32 s23, s30, 8
	s_and_b32 s25, s23, 0xc00
	v_add_u32_e32 v155, s25, v149
	ds_read_b32 v156, v155
	v_add_u32_e32 v146, s23, v150
	v_lshl_or_b32 v158, s49, 8, v151
	v_ashrrev_i32_e32 v147, 31, v146
	v_ashrrev_i32_e32 v159, 31, v158
	s_waitcnt lgkmcnt(0)
	v_pk_mul_f32 v[126:127], v[126:127], v[156:157] op_sel_hi:[1,0]
	v_pk_mul_f32 v[124:125], v[124:125], v[156:157] op_sel_hi:[1,0]
	v_pk_mul_f32 v[122:123], v[122:123], v[156:157] op_sel_hi:[1,0]
	v_pk_mul_f32 v[120:121], v[120:121], v[156:157] op_sel_hi:[1,0]
	v_pk_mul_f32 v[114:115], v[114:115], v[156:157] op_sel_hi:[1,0]
	v_max_f32_e32 v124, 0, v124
	v_max_f32_e32 v120, 0, v120
	v_max_f32_e32 v125, 0, v125
	v_max_f32_e32 v121, 0, v121
	v_max_f32_e32 v126, 0, v126
	v_max_f32_e32 v122, 0, v122
	v_max_f32_e32 v127, 0, v127
	v_max_f32_e32 v123, 0, v123
	v_pk_mul_f32 v[118:119], v[118:119], v[156:157] op_sel_hi:[1,0]
	v_pk_mul_f32 v[116:117], v[116:117], v[156:157] op_sel_hi:[1,0]
	v_pk_mul_f32 v[112:113], v[112:113], v[156:157] op_sel_hi:[1,0]
	v_max_f32_e32 v114, 0, v114
	v_mul_f32_e32 v124, v124, v124
	v_mul_f32_e32 v120, v120, v120
	v_mul_f32_e32 v125, v125, v125
	v_mul_f32_e32 v121, v121, v121
	v_mul_f32_e32 v126, v126, v126
	v_mul_f32_e32 v122, v122, v122
	v_mul_f32_e32 v127, v127, v127
	v_mul_f32_e32 v123, v123, v123
	v_max_f32_e32 v116, 0, v116
	v_max_f32_e32 v112, 0, v112
	v_max_f32_e32 v117, 0, v117
	v_max_f32_e32 v113, 0, v113
	v_max_f32_e32 v118, 0, v118
	v_mul_f32_e32 v114, v114, v114
	v_max_f32_e32 v119, 0, v119
	v_max_f32_e32 v115, 0, v115
	v_cvt_pk_bf16_f32 v124, v124, v125
	v_cvt_pk_bf16_f32 v125, v126, v127
	v_cvt_pk_bf16_f32 v120, v120, v121
	v_cvt_pk_bf16_f32 v121, v122, v123
	v_mul_f32_e32 v116, v116, v116
	v_mul_f32_e32 v112, v112, v112
	v_mul_f32_e32 v117, v117, v117
	v_mul_f32_e32 v113, v113, v113
	v_mul_f32_e32 v118, v118, v118
	v_mul_f32_e32 v119, v119, v119
	v_mul_f32_e32 v115, v115, v115
	v_cvt_pk_bf16_f32 v122, v116, v117
	v_cvt_pk_bf16_f32 v123, v118, v119
	v_cvt_pk_bf16_f32 v126, v112, v113
	v_cvt_pk_bf16_f32 v127, v114, v115
	s_nop 0
	v_cndmask_b32_e64 v114, v120, v126, s[0:1]
	v_cndmask_b32_e64 v112, v121, v127, s[0:1]
	v_cndmask_b32_e64 v113, v125, v123, s[0:1]
	v_mov_b32_dpp v160, v114 quad_perm:[1,0,3,2] row_mask:0xf bank_mask:0xf bound_ctrl:1
	v_cndmask_b32_e64 v116, v160, v120, s[0:1]
	ds_read_b32 v120, v155 offset:64
	v_cndmask_b32_e64 v115, v124, v122, s[0:1]
	v_mov_b32_dpp v157, v113 quad_perm:[1,0,3,2] row_mask:0xf bank_mask:0xf bound_ctrl:1
	v_mov_b32_dpp v161, v112 quad_perm:[1,0,3,2] row_mask:0xf bank_mask:0xf bound_ctrl:1
	v_lshlrev_b64 v[112:113], 13, v[146:147]
	v_mov_b32_dpp v156, v115 quad_perm:[1,0,3,2] row_mask:0xf bank_mask:0xf bound_ctrl:1
	v_lshl_add_u64 v[114:115], s[60:61], 0, v[112:113]
	v_lshlrev_b64 v[112:113], 1, v[158:159]
	v_lshl_add_u64 v[114:115], v[114:115], 0, v[112:113]
	v_lshl_add_u64 v[118:119], v[114:115], 0, v[136:137]
	v_cndmask_b32_e64 v115, v157, v125, s[0:1]
	v_cndmask_b32_e64 v117, v161, v121, s[0:1]
	v_cndmask_b32_e64 v114, v156, v124, s[0:1]
	s_waitcnt lgkmcnt(0)
	v_pk_mul_f32 v[108:109], v[108:109], v[120:121] op_sel_hi:[1,0]
	v_pk_mul_f32 v[106:107], v[106:107], v[120:121] op_sel_hi:[1,0]
	v_pk_mul_f32 v[104:105], v[104:105], v[120:121] op_sel_hi:[1,0]
	v_pk_mul_f32 v[102:103], v[102:103], v[120:121] op_sel_hi:[1,0]
	v_pk_mul_f32 v[96:97], v[96:97], v[120:121] op_sel_hi:[1,0]
	global_store_dwordx4 v[118:119], v[114:117], off nt
	v_add_co_u32_e32 v118, vcc, s43, v118
	v_pk_mul_f32 v[110:111], v[110:111], v[120:121] op_sel_hi:[1,0]
	v_max_f32_e32 v108, 0, v108
	v_max_f32_e32 v104, 0, v104
	v_max_f32_e32 v109, 0, v109
	v_max_f32_e32 v105, 0, v105
	v_max_f32_e32 v106, 0, v106
	v_max_f32_e32 v107, 0, v107
	v_pk_mul_f32 v[100:101], v[100:101], v[120:121] op_sel_hi:[1,0]
	v_pk_mul_f32 v[98:99], v[98:99], v[120:121] op_sel_hi:[1,0]
	v_max_f32_e32 v96, 0, v96
	v_max_f32_e32 v97, 0, v97
	v_max_f32_e32 v102, 0, v102
	v_max_f32_e32 v103, 0, v103
	v_cndmask_b32_e64 v115, v123, v157, s[0:1]
	v_cndmask_b32_e64 v117, v127, v161, s[0:1]
	v_cndmask_b32_e64 v114, v122, v156, s[0:1]
	v_cndmask_b32_e64 v116, v126, v160, s[0:1]
	v_addc_co_u32_e32 v119, vcc, 0, v119, vcc
	v_mul_f32_e32 v108, v108, v108
	v_mul_f32_e32 v104, v104, v104
	v_mul_f32_e32 v109, v109, v109
	v_mul_f32_e32 v105, v105, v105
	v_max_f32_e32 v110, 0, v110
	v_mul_f32_e32 v106, v106, v106
	v_max_f32_e32 v111, 0, v111
	v_mul_f32_e32 v107, v107, v107
	v_max_f32_e32 v100, 0, v100
	v_mul_f32_e32 v96, v96, v96
	v_max_f32_e32 v101, 0, v101
	v_mul_f32_e32 v97, v97, v97
	v_max_f32_e32 v98, 0, v98
	v_mul_f32_e32 v102, v102, v102
	v_max_f32_e32 v99, 0, v99
	v_mul_f32_e32 v103, v103, v103
	global_store_dwordx4 v[118:119], v[114:117], off nt
	v_mul_f32_e32 v110, v110, v110
	v_mul_f32_e32 v111, v111, v111
	v_cvt_pk_bf16_f32 v108, v108, v109
	v_cvt_pk_bf16_f32 v109, v110, v111
	v_cvt_pk_bf16_f32 v104, v104, v105
	v_cvt_pk_bf16_f32 v105, v106, v107
	v_mul_f32_e32 v100, v100, v100
	v_mul_f32_e32 v101, v101, v101
	v_mul_f32_e32 v98, v98, v98
	v_mul_f32_e32 v99, v99, v99
	v_cvt_pk_bf16_f32 v106, v100, v101
	v_cvt_pk_bf16_f32 v102, v102, v103
	v_cvt_pk_bf16_f32 v103, v96, v97
	v_cvt_pk_bf16_f32 v107, v98, v99
	v_or_b32_e32 v96, 16, v146
	v_cndmask_b32_e64 v97, v105, v107, s[0:1]
	v_cndmask_b32_e64 v98, v109, v102, s[0:1]
	v_cndmask_b32_e64 v99, v104, v103, s[0:1]
	v_mov_b32_dpp v115, v97 quad_perm:[1,0,3,2] row_mask:0xf bank_mask:0xf bound_ctrl:1
	v_ashrrev_i32_e32 v97, 31, v96
	v_lshlrev_b64 v[96:97], 13, v[96:97]
	v_cndmask_b32_e64 v100, v108, v106, s[0:1]
	v_lshl_add_u64 v[96:97], s[60:61], 0, v[96:97]
	v_mov_b32_dpp v111, v98 quad_perm:[1,0,3,2] row_mask:0xf bank_mask:0xf bound_ctrl:1
	v_mov_b32_dpp v110, v100 quad_perm:[1,0,3,2] row_mask:0xf bank_mask:0xf bound_ctrl:1
	v_mov_b32_dpp v114, v99 quad_perm:[1,0,3,2] row_mask:0xf bank_mask:0xf bound_ctrl:1
	v_lshl_add_u64 v[96:97], v[96:97], 0, v[112:113]
	v_lshl_add_u64 v[100:101], v[96:97], 0, v[136:137]
	v_cndmask_b32_e64 v97, v111, v109, s[0:1]
	v_cndmask_b32_e64 v99, v115, v105, s[0:1]
	v_cndmask_b32_e64 v96, v110, v108, s[0:1]
	v_cndmask_b32_e64 v98, v114, v104, s[0:1]
	global_store_dwordx4 v[100:101], v[96:99], off nt
	v_add_co_u32_e32 v100, vcc, s43, v100
	s_nop 0
	v_cndmask_b32_e64 v97, v102, v111, s[0:1]
	ds_read_b32 v102, v155 offset:128
	v_cndmask_b32_e64 v99, v107, v115, s[0:1]
	v_cndmask_b32_e64 v96, v106, v110, s[0:1]
	v_cndmask_b32_e64 v98, v103, v114, s[0:1]
	v_addc_co_u32_e32 v101, vcc, 0, v101, vcc
	s_waitcnt lgkmcnt(0)
	v_pk_mul_f32 v[92:93], v[92:93], v[102:103] op_sel_hi:[1,0]
	v_pk_mul_f32 v[90:91], v[90:91], v[102:103] op_sel_hi:[1,0]
	v_pk_mul_f32 v[88:89], v[88:89], v[102:103] op_sel_hi:[1,0]
	v_pk_mul_f32 v[86:87], v[86:87], v[102:103] op_sel_hi:[1,0]
	v_pk_mul_f32 v[80:81], v[80:81], v[102:103] op_sel_hi:[1,0]
	v_pk_mul_f32 v[94:95], v[94:95], v[102:103] op_sel_hi:[1,0]
	v_max_f32_e32 v92, 0, v92
	v_max_f32_e32 v88, 0, v88
	v_max_f32_e32 v93, 0, v93
	v_max_f32_e32 v89, 0, v89
	v_max_f32_e32 v90, 0, v90
	v_max_f32_e32 v91, 0, v91
	v_pk_mul_f32 v[84:85], v[84:85], v[102:103] op_sel_hi:[1,0]
	v_pk_mul_f32 v[82:83], v[82:83], v[102:103] op_sel_hi:[1,0]
	v_max_f32_e32 v80, 0, v80
	v_max_f32_e32 v81, 0, v81
	v_max_f32_e32 v86, 0, v86
	v_max_f32_e32 v87, 0, v87
	v_mul_f32_e32 v92, v92, v92
	v_mul_f32_e32 v88, v88, v88
	v_mul_f32_e32 v93, v93, v93
	v_mul_f32_e32 v89, v89, v89
	v_max_f32_e32 v94, 0, v94
	v_mul_f32_e32 v90, v90, v90
	v_max_f32_e32 v95, 0, v95
	v_mul_f32_e32 v91, v91, v91
	v_max_f32_e32 v84, 0, v84
	v_mul_f32_e32 v80, v80, v80
	v_max_f32_e32 v85, 0, v85
	v_mul_f32_e32 v81, v81, v81
	v_max_f32_e32 v82, 0, v82
	v_mul_f32_e32 v86, v86, v86
	v_max_f32_e32 v83, 0, v83
	v_mul_f32_e32 v87, v87, v87
	global_store_dwordx4 v[100:101], v[96:99], off nt
	v_mul_f32_e32 v94, v94, v94
	v_mul_f32_e32 v95, v95, v95
	v_cvt_pk_bf16_f32 v92, v92, v93
	v_cvt_pk_bf16_f32 v93, v94, v95
	v_cvt_pk_bf16_f32 v88, v88, v89
	v_cvt_pk_bf16_f32 v89, v90, v91
	v_mul_f32_e32 v84, v84, v84
	v_mul_f32_e32 v85, v85, v85
	v_mul_f32_e32 v82, v82, v82
	v_mul_f32_e32 v83, v83, v83
	v_cvt_pk_bf16_f32 v90, v84, v85
	v_cvt_pk_bf16_f32 v86, v86, v87
	v_cvt_pk_bf16_f32 v87, v80, v81
	v_cvt_pk_bf16_f32 v91, v82, v83
	v_or_b32_e32 v80, 32, v146
	v_cndmask_b32_e64 v81, v89, v91, s[0:1]
	v_cndmask_b32_e64 v82, v93, v86, s[0:1]
	v_cndmask_b32_e64 v83, v88, v87, s[0:1]
	v_mov_b32_dpp v97, v81 quad_perm:[1,0,3,2] row_mask:0xf bank_mask:0xf bound_ctrl:1
	v_ashrrev_i32_e32 v81, 31, v80
	v_lshlrev_b64 v[80:81], 13, v[80:81]
	v_cndmask_b32_e64 v84, v92, v90, s[0:1]
	v_lshl_add_u64 v[80:81], s[60:61], 0, v[80:81]
	v_mov_b32_dpp v95, v82 quad_perm:[1,0,3,2] row_mask:0xf bank_mask:0xf bound_ctrl:1
	v_mov_b32_dpp v94, v84 quad_perm:[1,0,3,2] row_mask:0xf bank_mask:0xf bound_ctrl:1
	v_mov_b32_dpp v96, v83 quad_perm:[1,0,3,2] row_mask:0xf bank_mask:0xf bound_ctrl:1
	v_lshl_add_u64 v[80:81], v[80:81], 0, v[112:113]
	v_lshl_add_u64 v[84:85], v[80:81], 0, v[136:137]
	v_cndmask_b32_e64 v81, v95, v93, s[0:1]
	v_cndmask_b32_e64 v83, v97, v89, s[0:1]
	v_cndmask_b32_e64 v80, v94, v92, s[0:1]
	v_cndmask_b32_e64 v82, v96, v88, s[0:1]
	global_store_dwordx4 v[84:85], v[80:83], off nt
	v_add_co_u32_e32 v84, vcc, s43, v84
	s_nop 0
	v_cndmask_b32_e64 v81, v86, v95, s[0:1]
	ds_read_b32 v86, v155 offset:192
	v_cndmask_b32_e64 v83, v91, v97, s[0:1]
	v_cndmask_b32_e64 v80, v90, v94, s[0:1]
	v_cndmask_b32_e64 v82, v87, v96, s[0:1]
	v_addc_co_u32_e32 v85, vcc, 0, v85, vcc
	s_waitcnt lgkmcnt(0)
	v_pk_mul_f32 v[76:77], v[76:77], v[86:87] op_sel_hi:[1,0]
	v_pk_mul_f32 v[74:75], v[74:75], v[86:87] op_sel_hi:[1,0]
	v_pk_mul_f32 v[72:73], v[72:73], v[86:87] op_sel_hi:[1,0]
	v_pk_mul_f32 v[70:71], v[70:71], v[86:87] op_sel_hi:[1,0]
	v_pk_mul_f32 v[64:65], v[64:65], v[86:87] op_sel_hi:[1,0]
	v_pk_mul_f32 v[78:79], v[78:79], v[86:87] op_sel_hi:[1,0]
	v_max_f32_e32 v76, 0, v76
	v_max_f32_e32 v72, 0, v72
	v_max_f32_e32 v77, 0, v77
	v_max_f32_e32 v73, 0, v73
	v_max_f32_e32 v74, 0, v74
	v_max_f32_e32 v75, 0, v75
	v_pk_mul_f32 v[68:69], v[68:69], v[86:87] op_sel_hi:[1,0]
	v_pk_mul_f32 v[66:67], v[66:67], v[86:87] op_sel_hi:[1,0]
	v_max_f32_e32 v64, 0, v64
	v_max_f32_e32 v65, 0, v65
	v_max_f32_e32 v70, 0, v70
	v_max_f32_e32 v71, 0, v71
	v_mul_f32_e32 v76, v76, v76
	v_mul_f32_e32 v72, v72, v72
	v_mul_f32_e32 v77, v77, v77
	v_mul_f32_e32 v73, v73, v73
	v_max_f32_e32 v78, 0, v78
	v_mul_f32_e32 v74, v74, v74
	v_max_f32_e32 v79, 0, v79
	v_mul_f32_e32 v75, v75, v75
	v_max_f32_e32 v68, 0, v68
	v_mul_f32_e32 v64, v64, v64
	v_max_f32_e32 v69, 0, v69
	v_mul_f32_e32 v65, v65, v65
	v_max_f32_e32 v66, 0, v66
	v_mul_f32_e32 v70, v70, v70
	v_max_f32_e32 v67, 0, v67
	v_mul_f32_e32 v71, v71, v71
	global_store_dwordx4 v[84:85], v[80:83], off nt
	v_mul_f32_e32 v78, v78, v78
	v_mul_f32_e32 v79, v79, v79
	v_cvt_pk_bf16_f32 v76, v76, v77
	v_cvt_pk_bf16_f32 v77, v78, v79
	v_cvt_pk_bf16_f32 v72, v72, v73
	v_cvt_pk_bf16_f32 v73, v74, v75
	v_mul_f32_e32 v68, v68, v68
	v_mul_f32_e32 v69, v69, v69
	v_mul_f32_e32 v66, v66, v66
	v_mul_f32_e32 v67, v67, v67
	v_cvt_pk_bf16_f32 v74, v68, v69
	v_cvt_pk_bf16_f32 v70, v70, v71
	v_cvt_pk_bf16_f32 v71, v64, v65
	v_cvt_pk_bf16_f32 v75, v66, v67
	v_or_b32_e32 v64, 48, v146
	v_cndmask_b32_e64 v65, v73, v75, s[0:1]
	v_cndmask_b32_e64 v66, v77, v70, s[0:1]
	v_cndmask_b32_e64 v67, v72, v71, s[0:1]
	v_mov_b32_dpp v81, v65 quad_perm:[1,0,3,2] row_mask:0xf bank_mask:0xf bound_ctrl:1
	v_ashrrev_i32_e32 v65, 31, v64
	v_lshlrev_b64 v[64:65], 13, v[64:65]
	v_cndmask_b32_e64 v68, v76, v74, s[0:1]
	v_lshl_add_u64 v[64:65], s[60:61], 0, v[64:65]
	v_mov_b32_dpp v79, v66 quad_perm:[1,0,3,2] row_mask:0xf bank_mask:0xf bound_ctrl:1
	v_mov_b32_dpp v78, v68 quad_perm:[1,0,3,2] row_mask:0xf bank_mask:0xf bound_ctrl:1
	v_mov_b32_dpp v80, v67 quad_perm:[1,0,3,2] row_mask:0xf bank_mask:0xf bound_ctrl:1
	v_lshl_add_u64 v[64:65], v[64:65], 0, v[112:113]
	v_lshl_add_u64 v[68:69], v[64:65], 0, v[136:137]
	v_cndmask_b32_e64 v65, v79, v77, s[0:1]
	v_cndmask_b32_e64 v67, v81, v73, s[0:1]
	v_cndmask_b32_e64 v64, v78, v76, s[0:1]
	v_cndmask_b32_e64 v66, v80, v72, s[0:1]
	global_store_dwordx4 v[68:69], v[64:67], off nt
	v_add_co_u32_e32 v68, vcc, s43, v68
	s_nop 0
	v_cndmask_b32_e64 v65, v70, v79, s[0:1]
	ds_read_b32 v70, v155 offset:512
	v_cndmask_b32_e64 v67, v75, v81, s[0:1]
	v_cndmask_b32_e64 v64, v74, v78, s[0:1]
	v_cndmask_b32_e64 v66, v71, v80, s[0:1]
	v_addc_co_u32_e32 v69, vcc, 0, v69, vcc
	s_waitcnt lgkmcnt(0)
	v_pk_mul_f32 v[60:61], v[60:61], v[70:71] op_sel_hi:[1,0]
	v_pk_mul_f32 v[58:59], v[58:59], v[70:71] op_sel_hi:[1,0]
	v_pk_mul_f32 v[56:57], v[56:57], v[70:71] op_sel_hi:[1,0]
	v_pk_mul_f32 v[54:55], v[54:55], v[70:71] op_sel_hi:[1,0]
	v_pk_mul_f32 v[48:49], v[48:49], v[70:71] op_sel_hi:[1,0]
	v_pk_mul_f32 v[62:63], v[62:63], v[70:71] op_sel_hi:[1,0]
	v_max_f32_e32 v60, 0, v60
	v_max_f32_e32 v56, 0, v56
	v_max_f32_e32 v61, 0, v61
	v_max_f32_e32 v57, 0, v57
	v_max_f32_e32 v58, 0, v58
	v_max_f32_e32 v59, 0, v59
	v_pk_mul_f32 v[52:53], v[52:53], v[70:71] op_sel_hi:[1,0]
	v_pk_mul_f32 v[50:51], v[50:51], v[70:71] op_sel_hi:[1,0]
	v_max_f32_e32 v48, 0, v48
	v_max_f32_e32 v49, 0, v49
	v_max_f32_e32 v54, 0, v54
	v_max_f32_e32 v55, 0, v55
	global_store_dwordx4 v[68:69], v[64:67], off nt
	v_mul_f32_e32 v60, v60, v60
	v_mul_f32_e32 v56, v56, v56
	v_add_u32_e32 v64, 0x80, v146
	v_mul_f32_e32 v61, v61, v61
	v_mul_f32_e32 v57, v57, v57
	v_max_f32_e32 v62, 0, v62
	v_mul_f32_e32 v58, v58, v58
	v_max_f32_e32 v63, 0, v63
	v_mul_f32_e32 v59, v59, v59
	v_max_f32_e32 v52, 0, v52
	v_mul_f32_e32 v48, v48, v48
	v_max_f32_e32 v53, 0, v53
	v_mul_f32_e32 v49, v49, v49
	v_max_f32_e32 v50, 0, v50
	v_mul_f32_e32 v54, v54, v54
	v_max_f32_e32 v51, 0, v51
	v_mul_f32_e32 v55, v55, v55
	v_mul_f32_e32 v62, v62, v62
	v_mul_f32_e32 v63, v63, v63
	v_cvt_pk_bf16_f32 v60, v60, v61
	v_cvt_pk_bf16_f32 v61, v62, v63
	v_cvt_pk_bf16_f32 v56, v56, v57
	v_cvt_pk_bf16_f32 v57, v58, v59
	v_mul_f32_e32 v52, v52, v52
	v_mul_f32_e32 v53, v53, v53
	v_mul_f32_e32 v50, v50, v50
	v_mul_f32_e32 v51, v51, v51
	v_cvt_pk_bf16_f32 v58, v52, v53
	v_cvt_pk_bf16_f32 v54, v54, v55
	v_cvt_pk_bf16_f32 v55, v48, v49
	v_cvt_pk_bf16_f32 v59, v50, v51
	v_ashrrev_i32_e32 v65, 31, v64
	v_cndmask_b32_e64 v48, v57, v59, s[0:1]
	v_cndmask_b32_e64 v49, v61, v54, s[0:1]
	v_cndmask_b32_e64 v50, v56, v55, s[0:1]
	v_mov_b32_dpp v67, v48 quad_perm:[1,0,3,2] row_mask:0xf bank_mask:0xf bound_ctrl:1
	v_mov_b32_dpp v63, v49 quad_perm:[1,0,3,2] row_mask:0xf bank_mask:0xf bound_ctrl:1
	v_lshlrev_b64 v[48:49], 13, v[64:65]
	v_cndmask_b32_e64 v51, v60, v58, s[0:1]
	v_lshl_add_u64 v[48:49], s[60:61], 0, v[48:49]
	v_mov_b32_dpp v66, v50 quad_perm:[1,0,3,2] row_mask:0xf bank_mask:0xf bound_ctrl:1
	v_mov_b32_dpp v62, v51 quad_perm:[1,0,3,2] row_mask:0xf bank_mask:0xf bound_ctrl:1
	v_lshl_add_u64 v[48:49], v[48:49], 0, v[112:113]
	v_lshl_add_u64 v[52:53], v[48:49], 0, v[136:137]
	v_cndmask_b32_e64 v49, v63, v61, s[0:1]
	v_cndmask_b32_e64 v51, v67, v57, s[0:1]
	v_cndmask_b32_e64 v48, v62, v60, s[0:1]
	v_cndmask_b32_e64 v50, v66, v56, s[0:1]
	global_store_dwordx4 v[52:53], v[48:51], off nt
	v_add_co_u32_e32 v52, vcc, s43, v52
	s_nop 0
	v_cndmask_b32_e64 v49, v54, v63, s[0:1]
	ds_read_b32 v54, v155 offset:576
	v_cndmask_b32_e64 v51, v59, v67, s[0:1]
	v_cndmask_b32_e64 v48, v58, v62, s[0:1]
	v_cndmask_b32_e64 v50, v55, v66, s[0:1]
	v_addc_co_u32_e32 v53, vcc, 0, v53, vcc
	s_waitcnt lgkmcnt(0)
	v_pk_mul_f32 v[44:45], v[44:45], v[54:55] op_sel_hi:[1,0]
	v_pk_mul_f32 v[42:43], v[42:43], v[54:55] op_sel_hi:[1,0]
	v_pk_mul_f32 v[40:41], v[40:41], v[54:55] op_sel_hi:[1,0]
	v_pk_mul_f32 v[38:39], v[38:39], v[54:55] op_sel_hi:[1,0]
	v_pk_mul_f32 v[32:33], v[32:33], v[54:55] op_sel_hi:[1,0]
	v_pk_mul_f32 v[46:47], v[46:47], v[54:55] op_sel_hi:[1,0]
	v_max_f32_e32 v44, 0, v44
	v_max_f32_e32 v40, 0, v40
	v_max_f32_e32 v45, 0, v45
	v_max_f32_e32 v41, 0, v41
	v_max_f32_e32 v42, 0, v42
	v_max_f32_e32 v43, 0, v43
	v_pk_mul_f32 v[36:37], v[36:37], v[54:55] op_sel_hi:[1,0]
	v_pk_mul_f32 v[34:35], v[34:35], v[54:55] op_sel_hi:[1,0]
	v_max_f32_e32 v32, 0, v32
	v_max_f32_e32 v33, 0, v33
	v_max_f32_e32 v38, 0, v38
	v_max_f32_e32 v39, 0, v39
	v_mul_f32_e32 v44, v44, v44
	v_mul_f32_e32 v40, v40, v40
	v_mul_f32_e32 v45, v45, v45
	v_mul_f32_e32 v41, v41, v41
	v_max_f32_e32 v46, 0, v46
	v_mul_f32_e32 v42, v42, v42
	v_max_f32_e32 v47, 0, v47
	v_mul_f32_e32 v43, v43, v43
	v_max_f32_e32 v36, 0, v36
	v_mul_f32_e32 v32, v32, v32
	v_max_f32_e32 v37, 0, v37
	v_mul_f32_e32 v33, v33, v33
	v_max_f32_e32 v34, 0, v34
	v_mul_f32_e32 v38, v38, v38
	v_max_f32_e32 v35, 0, v35
	v_mul_f32_e32 v39, v39, v39
	global_store_dwordx4 v[52:53], v[48:51], off nt
	v_mul_f32_e32 v46, v46, v46
	v_mul_f32_e32 v47, v47, v47
	v_cvt_pk_bf16_f32 v44, v44, v45
	v_cvt_pk_bf16_f32 v45, v46, v47
	v_cvt_pk_bf16_f32 v40, v40, v41
	v_cvt_pk_bf16_f32 v41, v42, v43
	v_mul_f32_e32 v36, v36, v36
	v_mul_f32_e32 v37, v37, v37
	v_mul_f32_e32 v34, v34, v34
	v_mul_f32_e32 v35, v35, v35
	v_cvt_pk_bf16_f32 v42, v36, v37
	v_cvt_pk_bf16_f32 v38, v38, v39
	v_cvt_pk_bf16_f32 v39, v32, v33
	v_cvt_pk_bf16_f32 v43, v34, v35
	v_add_u32_e32 v32, 0x90, v146
	v_cndmask_b32_e64 v33, v41, v43, s[0:1]
	v_cndmask_b32_e64 v34, v45, v38, s[0:1]
	v_cndmask_b32_e64 v35, v40, v39, s[0:1]
	v_mov_b32_dpp v49, v33 quad_perm:[1,0,3,2] row_mask:0xf bank_mask:0xf bound_ctrl:1
	v_ashrrev_i32_e32 v33, 31, v32
	v_lshlrev_b64 v[32:33], 13, v[32:33]
	v_cndmask_b32_e64 v36, v44, v42, s[0:1]
	v_lshl_add_u64 v[32:33], s[60:61], 0, v[32:33]
	v_mov_b32_dpp v47, v34 quad_perm:[1,0,3,2] row_mask:0xf bank_mask:0xf bound_ctrl:1
	v_mov_b32_dpp v46, v36 quad_perm:[1,0,3,2] row_mask:0xf bank_mask:0xf bound_ctrl:1
	v_mov_b32_dpp v48, v35 quad_perm:[1,0,3,2] row_mask:0xf bank_mask:0xf bound_ctrl:1
	v_lshl_add_u64 v[32:33], v[32:33], 0, v[112:113]
	v_lshl_add_u64 v[36:37], v[32:33], 0, v[136:137]
	v_cndmask_b32_e64 v33, v47, v45, s[0:1]
	v_cndmask_b32_e64 v35, v49, v41, s[0:1]
	v_cndmask_b32_e64 v32, v46, v44, s[0:1]
	v_cndmask_b32_e64 v34, v48, v40, s[0:1]
	global_store_dwordx4 v[36:37], v[32:35], off nt
	v_add_co_u32_e32 v36, vcc, s43, v36
	s_nop 0
	v_cndmask_b32_e64 v33, v38, v47, s[0:1]
	ds_read_b32 v38, v155 offset:640
	v_cndmask_b32_e64 v35, v43, v49, s[0:1]
	v_cndmask_b32_e64 v32, v42, v46, s[0:1]
	v_cndmask_b32_e64 v34, v39, v48, s[0:1]
	v_addc_co_u32_e32 v37, vcc, 0, v37, vcc
	s_waitcnt lgkmcnt(0)
	v_pk_mul_f32 v[28:29], v[28:29], v[38:39] op_sel_hi:[1,0]
	v_pk_mul_f32 v[26:27], v[26:27], v[38:39] op_sel_hi:[1,0]
	v_pk_mul_f32 v[24:25], v[24:25], v[38:39] op_sel_hi:[1,0]
	v_pk_mul_f32 v[22:23], v[22:23], v[38:39] op_sel_hi:[1,0]
	v_pk_mul_f32 v[16:17], v[16:17], v[38:39] op_sel_hi:[1,0]
	v_pk_mul_f32 v[30:31], v[30:31], v[38:39] op_sel_hi:[1,0]
	v_max_f32_e32 v28, 0, v28
	v_max_f32_e32 v24, 0, v24
	v_max_f32_e32 v29, 0, v29
	v_max_f32_e32 v25, 0, v25
	v_max_f32_e32 v26, 0, v26
	v_max_f32_e32 v27, 0, v27
	v_pk_mul_f32 v[20:21], v[20:21], v[38:39] op_sel_hi:[1,0]
	v_pk_mul_f32 v[18:19], v[18:19], v[38:39] op_sel_hi:[1,0]
	v_max_f32_e32 v16, 0, v16
	v_max_f32_e32 v17, 0, v17
	v_max_f32_e32 v22, 0, v22
	v_max_f32_e32 v23, 0, v23
	v_mul_f32_e32 v28, v28, v28
	v_mul_f32_e32 v24, v24, v24
	v_mul_f32_e32 v29, v29, v29
	v_mul_f32_e32 v25, v25, v25
	v_max_f32_e32 v30, 0, v30
	v_mul_f32_e32 v26, v26, v26
	v_max_f32_e32 v31, 0, v31
	v_mul_f32_e32 v27, v27, v27
	v_max_f32_e32 v20, 0, v20
	v_mul_f32_e32 v16, v16, v16
	v_max_f32_e32 v21, 0, v21
	v_mul_f32_e32 v17, v17, v17
	v_max_f32_e32 v18, 0, v18
	v_mul_f32_e32 v22, v22, v22
	v_max_f32_e32 v19, 0, v19
	v_mul_f32_e32 v23, v23, v23
	global_store_dwordx4 v[36:37], v[32:35], off nt
	v_mul_f32_e32 v30, v30, v30
	v_mul_f32_e32 v31, v31, v31
	v_cvt_pk_bf16_f32 v28, v28, v29
	v_cvt_pk_bf16_f32 v29, v30, v31
	v_cvt_pk_bf16_f32 v24, v24, v25
	v_cvt_pk_bf16_f32 v25, v26, v27
	v_mul_f32_e32 v20, v20, v20
	v_mul_f32_e32 v21, v21, v21
	v_mul_f32_e32 v18, v18, v18
	v_mul_f32_e32 v19, v19, v19
	v_cvt_pk_bf16_f32 v26, v20, v21
	v_cvt_pk_bf16_f32 v22, v22, v23
	v_cvt_pk_bf16_f32 v23, v16, v17
	v_cvt_pk_bf16_f32 v27, v18, v19
	v_add_u32_e32 v16, 0xa0, v146
	v_cndmask_b32_e64 v17, v25, v27, s[0:1]
	v_cndmask_b32_e64 v18, v29, v22, s[0:1]
	v_cndmask_b32_e64 v19, v24, v23, s[0:1]
	v_mov_b32_dpp v33, v17 quad_perm:[1,0,3,2] row_mask:0xf bank_mask:0xf bound_ctrl:1
	v_ashrrev_i32_e32 v17, 31, v16
	v_lshlrev_b64 v[16:17], 13, v[16:17]
	v_cndmask_b32_e64 v20, v28, v26, s[0:1]
	v_lshl_add_u64 v[16:17], s[60:61], 0, v[16:17]
	v_mov_b32_dpp v31, v18 quad_perm:[1,0,3,2] row_mask:0xf bank_mask:0xf bound_ctrl:1
	v_mov_b32_dpp v30, v20 quad_perm:[1,0,3,2] row_mask:0xf bank_mask:0xf bound_ctrl:1
	v_mov_b32_dpp v32, v19 quad_perm:[1,0,3,2] row_mask:0xf bank_mask:0xf bound_ctrl:1
	v_lshl_add_u64 v[16:17], v[16:17], 0, v[112:113]
	v_lshl_add_u64 v[20:21], v[16:17], 0, v[136:137]
	v_cndmask_b32_e64 v17, v31, v29, s[0:1]
	v_cndmask_b32_e64 v19, v33, v25, s[0:1]
	v_cndmask_b32_e64 v16, v30, v28, s[0:1]
	v_cndmask_b32_e64 v18, v32, v24, s[0:1]
	global_store_dwordx4 v[20:21], v[16:19], off nt
	v_add_co_u32_e32 v20, vcc, s43, v20
	s_nop 0
	v_cndmask_b32_e64 v17, v22, v31, s[0:1]
	ds_read_b32 v22, v155 offset:704
	v_cndmask_b32_e64 v19, v27, v33, s[0:1]
	v_cndmask_b32_e64 v16, v26, v30, s[0:1]
	v_cndmask_b32_e64 v18, v23, v32, s[0:1]
	v_addc_co_u32_e32 v21, vcc, 0, v21, vcc
	s_waitcnt lgkmcnt(0)
	v_pk_mul_f32 v[12:13], v[12:13], v[22:23] op_sel_hi:[1,0]
	v_pk_mul_f32 v[10:11], v[10:11], v[22:23] op_sel_hi:[1,0]
	v_pk_mul_f32 v[8:9], v[8:9], v[22:23] op_sel_hi:[1,0]
	v_pk_mul_f32 v[6:7], v[6:7], v[22:23] op_sel_hi:[1,0]
	v_pk_mul_f32 v[0:1], v[0:1], v[22:23] op_sel_hi:[1,0]
	v_pk_mul_f32 v[14:15], v[14:15], v[22:23] op_sel_hi:[1,0]
	v_max_f32_e32 v12, 0, v12
	v_max_f32_e32 v8, 0, v8
	v_max_f32_e32 v13, 0, v13
	v_max_f32_e32 v9, 0, v9
	v_max_f32_e32 v10, 0, v10
	v_max_f32_e32 v11, 0, v11
	v_pk_mul_f32 v[4:5], v[4:5], v[22:23] op_sel_hi:[1,0]
	v_pk_mul_f32 v[2:3], v[2:3], v[22:23] op_sel_hi:[1,0]
	v_max_f32_e32 v0, 0, v0
	v_max_f32_e32 v1, 0, v1
	v_max_f32_e32 v6, 0, v6
	v_max_f32_e32 v7, 0, v7
	v_mul_f32_e32 v12, v12, v12
	v_mul_f32_e32 v8, v8, v8
	v_mul_f32_e32 v13, v13, v13
	v_mul_f32_e32 v9, v9, v9
	v_max_f32_e32 v14, 0, v14
	v_mul_f32_e32 v10, v10, v10
	v_max_f32_e32 v15, 0, v15
	v_mul_f32_e32 v11, v11, v11
	v_max_f32_e32 v4, 0, v4
	v_mul_f32_e32 v0, v0, v0
	v_max_f32_e32 v5, 0, v5
	v_mul_f32_e32 v1, v1, v1
	v_max_f32_e32 v2, 0, v2
	v_mul_f32_e32 v6, v6, v6
	v_max_f32_e32 v3, 0, v3
	v_mul_f32_e32 v7, v7, v7
	global_store_dwordx4 v[20:21], v[16:19], off nt
	v_mul_f32_e32 v14, v14, v14
	v_mul_f32_e32 v15, v15, v15
	v_cvt_pk_bf16_f32 v12, v12, v13
	v_cvt_pk_bf16_f32 v13, v14, v15
	v_cvt_pk_bf16_f32 v8, v8, v9
	v_cvt_pk_bf16_f32 v9, v10, v11
	v_mul_f32_e32 v4, v4, v4
	v_mul_f32_e32 v5, v5, v5
	v_mul_f32_e32 v2, v2, v2
	v_mul_f32_e32 v3, v3, v3
	v_cvt_pk_bf16_f32 v10, v4, v5
	v_cvt_pk_bf16_f32 v6, v6, v7
	v_cvt_pk_bf16_f32 v7, v0, v1
	v_cvt_pk_bf16_f32 v11, v2, v3
	v_add_u32_e32 v0, 0xb0, v146
	v_cndmask_b32_e64 v1, v9, v11, s[0:1]
	v_cndmask_b32_e64 v2, v13, v6, s[0:1]
	v_cndmask_b32_e64 v3, v8, v7, s[0:1]
	v_mov_b32_dpp v17, v1 quad_perm:[1,0,3,2] row_mask:0xf bank_mask:0xf bound_ctrl:1
	v_ashrrev_i32_e32 v1, 31, v0
	v_lshlrev_b64 v[0:1], 13, v[0:1]
	v_cndmask_b32_e64 v4, v12, v10, s[0:1]
	v_lshl_add_u64 v[0:1], s[60:61], 0, v[0:1]
	v_mov_b32_dpp v15, v2 quad_perm:[1,0,3,2] row_mask:0xf bank_mask:0xf bound_ctrl:1
	v_mov_b32_dpp v14, v4 quad_perm:[1,0,3,2] row_mask:0xf bank_mask:0xf bound_ctrl:1
	v_mov_b32_dpp v16, v3 quad_perm:[1,0,3,2] row_mask:0xf bank_mask:0xf bound_ctrl:1
	v_lshl_add_u64 v[0:1], v[0:1], 0, v[112:113]
	v_lshl_add_u64 v[4:5], v[0:1], 0, v[136:137]
	v_cndmask_b32_e64 v1, v15, v13, s[0:1]
	v_cndmask_b32_e64 v3, v17, v9, s[0:1]
	v_cndmask_b32_e64 v0, v14, v12, s[0:1]
	v_cndmask_b32_e64 v2, v16, v8, s[0:1]
	global_store_dwordx4 v[4:5], v[0:3], off nt
	v_add_co_u32_e32 v4, vcc, 0x2000, v4
	s_nop 0
	v_cndmask_b32_e64 v1, v6, v15, s[0:1]
	v_addc_co_u32_e32 v5, vcc, 0, v5, vcc
	v_cndmask_b32_e64 v3, v11, v17, s[0:1]
	v_cndmask_b32_e64 v0, v10, v14, s[0:1]
	v_cndmask_b32_e64 v2, v7, v16, s[0:1]
	s_andn2_b64 vcc, exec, s[6:7]
	s_mov_b64 s[6:7], -1
	global_store_dwordx4 v[4:5], v[0:3], off nt
	s_mov_b32 s98, 1
	s_cbranch_vccnz .LBB0_743
	s_andn2_b64 vcc, exec, s[10:11]
	s_cbranch_vccnz .LBB0_742
	s_barrier
	s_branch .LBB0_742

.LBB0_827:
	s_ashr_i32 s27, s26, 31
	s_lshl_b64 s[28:29], s[26:27], 21
	s_add_u32 s28, s60, s28
	s_addc_u32 s29, s61, s29
	s_and_b64 s[30:31], s[4:5], exec
	s_cselect_b32 s27, s29, s39
	s_cselect_b32 s54, s28, s38
	s_ashr_i32 s25, s24, 31
	s_lshl_b64 s[30:31], s[24:25], 21
	s_add_u32 s30, s12, s30
	s_addc_u32 s31, s13, s31
	s_and_b64 s[42:43], s[4:5], exec
	s_cselect_b32 s25, s31, s41
	s_cselect_b32 s55, s30, s40
	s_add_u32 s38, s38, 0x100080
	s_addc_u32 s39, s39, 0
	s_add_u32 s56, s40, 0x100
	s_addc_u32 s57, s41, 0
	s_mov_b32 s58, -2
	ds_read_b128 v[142:145], v195
	ds_read_b128 v[146:149], v195 offset:1024
	ds_read_b128 v[150:153], v195 offset:2048
	ds_read_b128 v[154:157], v195 offset:3072
	ds_read_b128 v[158:161], v196
	ds_read_b128 v[162:165], v196 offset:1024
	ds_read_b128 v[166:169], v196 offset:2048
	ds_read_b128 v[170:173], v196 offset:3072
	s_add_u32 s40, s38, 0xfff00080
	s_addc_u32 s41, s39, -1
	s_cmp_eq_u32 s58, 60
	s_cselect_b32 s43, s27, s41
	s_cselect_b32 s42, s54, s40
	s_cselect_b32 s41, s25, s57
	s_cselect_b32 s40, s55, s56
	v_lshl_add_u64 v[190:191], s[38:39], 0, v[134:135]
	s_add_i32 m0, s2, 0xc000
	ds_read_b128 v[174:177], v197
	ds_read_b128 v[178:181], v197 offset:1024
	ds_read_b128 v[182:185], v197 offset:2048
	ds_read_b128 v[186:189], v197 offset:3072
	ds_read_b128 v[198:201], v197 offset:4096
	ds_read_b128 v[202:205], v197 offset:5120
	ds_read_b128 v[206:209], v197 offset:6144
	ds_read_b128 v[210:213], v197 offset:7168
	global_load_lds_dwordx4 v[190:191], off
	v_lshl_add_u64 v[190:191], s[38:39], 0, v[136:137]
	s_add_i32 m0, s2, 0xe000
	s_nop 0
	global_load_lds_dwordx4 v[190:191], off
	s_cmp_eq_u32 s98, 0
	s_cbranch_scc1 .Lrx3_0n
	s_waitcnt vmcnt(40)
	s_branch .Lrx3_0j

.Lrx3_0j:
	s_waitcnt lgkmcnt(0)
	s_barrier
	s_setprio 1
	s_waitcnt lgkmcnt(0)
	v_mfma_f32_16x16x32_bf16 v[124:127], v[142:145], v[174:177], 0
	v_mfma_f32_16x16x32_bf16 v[124:127], v[146:149], v[178:181], v[124:127]
	v_mfma_f32_16x16x32_bf16 v[120:123], v[150:153], v[174:177], 0
	v_mfma_f32_16x16x32_bf16 v[120:123], v[154:157], v[178:181], v[120:123]
	v_mfma_f32_16x16x32_bf16 v[104:107], v[150:153], v[182:185], 0
	v_mfma_f32_16x16x32_bf16 v[104:107], v[154:157], v[186:189], v[104:107]
	v_mfma_f32_16x16x32_bf16 v[108:111], v[142:145], v[182:185], 0
	v_mfma_f32_16x16x32_bf16 v[108:111], v[146:149], v[186:189], v[108:111]
	v_mfma_f32_16x16x32_bf16 v[92:95], v[142:145], v[198:201], 0
	v_mfma_f32_16x16x32_bf16 v[92:95], v[146:149], v[202:205], v[92:95]
	v_mfma_f32_16x16x32_bf16 v[88:91], v[150:153], v[198:201], 0
	v_mfma_f32_16x16x32_bf16 v[88:91], v[154:157], v[202:205], v[88:91]
	v_mfma_f32_16x16x32_bf16 v[72:75], v[150:153], v[206:209], 0
	v_mfma_f32_16x16x32_bf16 v[72:75], v[154:157], v[210:213], v[72:75]
	v_mfma_f32_16x16x32_bf16 v[76:79], v[142:145], v[206:209], 0
	v_mfma_f32_16x16x32_bf16 v[76:79], v[146:149], v[210:213], v[76:79]
	s_setprio 0
	s_setprio 1
	v_mfma_f32_16x16x32_bf16 v[116:119], v[158:161], v[174:177], 0
	v_mfma_f32_16x16x32_bf16 v[116:119], v[162:165], v[178:181], v[116:119]
	v_mfma_f32_16x16x32_bf16 v[112:115], v[166:169], v[174:177], 0
	v_mfma_f32_16x16x32_bf16 v[112:115], v[170:173], v[178:181], v[112:115]
	v_mfma_f32_16x16x32_bf16 v[96:99], v[166:169], v[182:185], 0
	v_mfma_f32_16x16x32_bf16 v[96:99], v[170:173], v[186:189], v[96:99]
	v_mfma_f32_16x16x32_bf16 v[100:103], v[158:161], v[182:185], 0
	v_mfma_f32_16x16x32_bf16 v[100:103], v[162:165], v[186:189], v[100:103]
	v_mfma_f32_16x16x32_bf16 v[84:87], v[158:161], v[198:201], 0
	v_mfma_f32_16x16x32_bf16 v[84:87], v[162:165], v[202:205], v[84:87]
	v_mfma_f32_16x16x32_bf16 v[80:83], v[166:169], v[198:201], 0
	v_mfma_f32_16x16x32_bf16 v[80:83], v[170:173], v[202:205], v[80:83]
	v_mfma_f32_16x16x32_bf16 v[64:67], v[166:169], v[206:209], 0
	v_mfma_f32_16x16x32_bf16 v[64:67], v[170:173], v[210:213], v[64:67]
	v_mfma_f32_16x16x32_bf16 v[68:71], v[158:161], v[206:209], 0
	v_mfma_f32_16x16x32_bf16 v[68:71], v[162:165], v[210:213], v[68:71]
	s_setprio 0
	s_barrier
	s_add_i32 s59, s46, s3
	v_lshl_add_u64 v[190:191], s[40:41], 0, v[128:129]
	s_mov_b32 m0, s59
	ds_read_b128 v[174:177], v197 offset:16384
	ds_read_b128 v[178:181], v197 offset:17408
	ds_read_b128 v[182:185], v197 offset:18432
	ds_read_b128 v[186:189], v197 offset:19456
	ds_read_b128 v[198:201], v197 offset:20480
	ds_read_b128 v[202:205], v197 offset:21504
	ds_read_b128 v[206:209], v197 offset:22528
	ds_read_b128 v[210:213], v197 offset:23552
	global_load_lds_dwordx4 v[190:191], off
	s_add_i32 m0, s59, 0x2000
	s_add_u32 s62, s40, 0x100000
	v_lshl_add_u64 v[214:215], s[40:41], 0, v[130:131]
	s_addc_u32 s63, s41, 0
	s_add_i32 s59, s47, s3
	global_load_lds_dwordx4 v[214:215], off
	v_lshl_add_u64 v[216:217], s[62:63], 0, v[128:129]
	s_mov_b32 m0, s59
	v_lshl_add_u64 v[218:219], s[42:43], 0, v[130:131]
	global_load_lds_dwordx4 v[216:217], off
	v_lshl_add_u64 v[216:217], s[62:63], 0, v[130:131]
	s_add_i32 m0, s59, 0x2000
	s_nop 0
	global_load_lds_dwordx4 v[216:217], off
	v_lshl_add_u64 v[216:217], s[42:43], 0, v[128:129]
	s_mov_b32 m0, s2
	s_nop 0
	global_load_lds_dwordx4 v[216:217], off
	s_mov_b32 m0, s33
	s_nop 0
	global_load_lds_dwordx4 v[218:219], off
	s_cmp_eq_u32 s98, 0
	s_cbranch_scc1 .Lrx3_1n
	s_waitcnt vmcnt(40)
	s_mov_b32 s98, 0
	s_branch .Lrx3_1j

.Lrx3_1j:
	s_waitcnt lgkmcnt(0)
	s_barrier
	s_setprio 1
	s_waitcnt lgkmcnt(0)
	v_mfma_f32_16x16x32_bf16 v[60:63], v[142:145], v[174:177], 0
	v_mfma_f32_16x16x32_bf16 v[60:63], v[146:149], v[178:181], v[60:63]
	v_mfma_f32_16x16x32_bf16 v[56:59], v[150:153], v[174:177], 0
	v_mfma_f32_16x16x32_bf16 v[56:59], v[154:157], v[178:181], v[56:59]
	v_mfma_f32_16x16x32_bf16 v[40:43], v[150:153], v[182:185], 0
	v_mfma_f32_16x16x32_bf16 v[40:43], v[154:157], v[186:189], v[40:43]
	v_mfma_f32_16x16x32_bf16 v[44:47], v[142:145], v[182:185], 0
	v_mfma_f32_16x16x32_bf16 v[44:47], v[146:149], v[186:189], v[44:47]
	v_mfma_f32_16x16x32_bf16 v[28:31], v[142:145], v[198:201], 0
	v_mfma_f32_16x16x32_bf16 v[28:31], v[146:149], v[202:205], v[28:31]
	v_mfma_f32_16x16x32_bf16 v[24:27], v[150:153], v[198:201], 0
	v_mfma_f32_16x16x32_bf16 v[24:27], v[154:157], v[202:205], v[24:27]
	v_mfma_f32_16x16x32_bf16 v[8:11], v[150:153], v[206:209], 0
	v_mfma_f32_16x16x32_bf16 v[8:11], v[154:157], v[210:213], v[8:11]
	v_mfma_f32_16x16x32_bf16 v[12:15], v[142:145], v[206:209], 0
	v_mfma_f32_16x16x32_bf16 v[12:15], v[146:149], v[210:213], v[12:15]
	s_setprio 0
	s_setprio 1
	v_mfma_f32_16x16x32_bf16 v[52:55], v[158:161], v[174:177], 0
	v_mfma_f32_16x16x32_bf16 v[52:55], v[162:165], v[178:181], v[52:55]
	v_mfma_f32_16x16x32_bf16 v[48:51], v[166:169], v[174:177], 0
	v_mfma_f32_16x16x32_bf16 v[48:51], v[170:173], v[178:181], v[48:51]
	v_mfma_f32_16x16x32_bf16 v[32:35], v[166:169], v[182:185], 0
	v_mfma_f32_16x16x32_bf16 v[32:35], v[170:173], v[186:189], v[32:35]
	v_mfma_f32_16x16x32_bf16 v[36:39], v[158:161], v[182:185], 0
	v_mfma_f32_16x16x32_bf16 v[36:39], v[162:165], v[186:189], v[36:39]
	v_mfma_f32_16x16x32_bf16 v[20:23], v[158:161], v[198:201], 0
	v_mfma_f32_16x16x32_bf16 v[20:23], v[162:165], v[202:205], v[20:23]
	v_mfma_f32_16x16x32_bf16 v[16:19], v[166:169], v[198:201], 0
	v_mfma_f32_16x16x32_bf16 v[16:19], v[170:173], v[202:205], v[16:19]
	v_mfma_f32_16x16x32_bf16 v[0:3], v[166:169], v[206:209], 0
	v_mfma_f32_16x16x32_bf16 v[0:3], v[170:173], v[210:213], v[0:3]
	v_mfma_f32_16x16x32_bf16 v[4:7], v[158:161], v[206:209], 0
	v_mfma_f32_16x16x32_bf16 v[4:7], v[162:165], v[210:213], v[4:7]
	s_setprio 0
	s_barrier
	s_add_i32 s59, 0, 0x18000
	s_add_i32 s62, 0, 0x1c000
	v_add_u32_e32 v154, s59, v192
	v_add_u32_e32 v170, s62, v192
	ds_read_b128 v[142:145], v154
	ds_read_b128 v[146:149], v154 offset:1024
	ds_read_b128 v[150:153], v154 offset:2048
	ds_read_b128 v[154:157], v154 offset:3072
	ds_read_b128 v[158:161], v170
	ds_read_b128 v[162:165], v170 offset:1024
	ds_read_b128 v[166:169], v170 offset:2048
	ds_read_b128 v[170:173], v170 offset:3072
	s_add_u32 s42, s42, 0x100000
	s_addc_u32 s43, s43, 0
	s_mov_b32 m0, s34
	v_lshl_add_u64 v[220:221], s[42:43], 0, v[128:129]
	ds_read_b128 v[174:177], v197 offset:32768
	ds_read_b128 v[178:181], v197 offset:33792
	ds_read_b128 v[182:185], v197 offset:34816
	ds_read_b128 v[186:189], v197 offset:35840
	ds_read_b128 v[198:201], v197 offset:36864
	ds_read_b128 v[202:205], v197 offset:37888
	ds_read_b128 v[206:209], v197 offset:38912
	ds_read_b128 v[210:213], v197 offset:39936
	global_load_lds_dwordx4 v[220:221], off
	v_lshl_add_u64 v[220:221], s[42:43], 0, v[130:131]
	s_mov_b32 m0, s35
	s_nop 0
	global_load_lds_dwordx4 v[220:221], off
	s_waitcnt vmcnt(8)
	s_waitcnt lgkmcnt(0)
	s_barrier
	s_setprio 1
	s_waitcnt lgkmcnt(0)
	v_mfma_f32_16x16x32_bf16 v[124:127], v[142:145], v[174:177], v[124:127]
	v_mfma_f32_16x16x32_bf16 v[124:127], v[146:149], v[178:181], v[124:127]
	v_mfma_f32_16x16x32_bf16 v[120:123], v[150:153], v[174:177], v[120:123]
	v_mfma_f32_16x16x32_bf16 v[120:123], v[154:157], v[178:181], v[120:123]
	v_mfma_f32_16x16x32_bf16 v[104:107], v[150:153], v[182:185], v[104:107]
	v_mfma_f32_16x16x32_bf16 v[104:107], v[154:157], v[186:189], v[104:107]
	v_mfma_f32_16x16x32_bf16 v[108:111], v[142:145], v[182:185], v[108:111]
	v_mfma_f32_16x16x32_bf16 v[108:111], v[146:149], v[186:189], v[108:111]
	v_mfma_f32_16x16x32_bf16 v[92:95], v[142:145], v[198:201], v[92:95]
	v_mfma_f32_16x16x32_bf16 v[92:95], v[146:149], v[202:205], v[92:95]
	v_mfma_f32_16x16x32_bf16 v[88:91], v[150:153], v[198:201], v[88:91]
	v_mfma_f32_16x16x32_bf16 v[88:91], v[154:157], v[202:205], v[88:91]
	v_mfma_f32_16x16x32_bf16 v[72:75], v[150:153], v[206:209], v[72:75]
	v_mfma_f32_16x16x32_bf16 v[72:75], v[154:157], v[210:213], v[72:75]
	v_mfma_f32_16x16x32_bf16 v[76:79], v[142:145], v[206:209], v[76:79]
	v_mfma_f32_16x16x32_bf16 v[76:79], v[146:149], v[210:213], v[76:79]
	s_setprio 0
	s_setprio 1
	v_mfma_f32_16x16x32_bf16 v[116:119], v[158:161], v[174:177], v[116:119]
	v_mfma_f32_16x16x32_bf16 v[116:119], v[162:165], v[178:181], v[116:119]
	v_mfma_f32_16x16x32_bf16 v[112:115], v[166:169], v[174:177], v[112:115]
	v_mfma_f32_16x16x32_bf16 v[112:115], v[170:173], v[178:181], v[112:115]
	v_mfma_f32_16x16x32_bf16 v[96:99], v[166:169], v[182:185], v[96:99]
	v_mfma_f32_16x16x32_bf16 v[96:99], v[170:173], v[186:189], v[96:99]
	v_mfma_f32_16x16x32_bf16 v[100:103], v[158:161], v[182:185], v[100:103]
	v_mfma_f32_16x16x32_bf16 v[100:103], v[162:165], v[186:189], v[100:103]
	v_mfma_f32_16x16x32_bf16 v[84:87], v[158:161], v[198:201], v[84:87]
	v_mfma_f32_16x16x32_bf16 v[84:87], v[162:165], v[202:205], v[84:87]
	v_mfma_f32_16x16x32_bf16 v[80:83], v[166:169], v[198:201], v[80:83]
	v_mfma_f32_16x16x32_bf16 v[80:83], v[170:173], v[202:205], v[80:83]
	v_mfma_f32_16x16x32_bf16 v[64:67], v[166:169], v[206:209], v[64:67]
	v_mfma_f32_16x16x32_bf16 v[64:67], v[170:173], v[210:213], v[64:67]
	v_mfma_f32_16x16x32_bf16 v[68:71], v[158:161], v[206:209], v[68:71]
	v_mfma_f32_16x16x32_bf16 v[68:71], v[162:165], v[210:213], v[68:71]
	s_setprio 0
	s_barrier
	s_add_i32 s42, s59, s3
	v_lshl_add_u64 v[190:191], v[190:191], 0, s[8:9]
	s_mov_b32 m0, s42
	ds_read_b128 v[174:177], v197 offset:49152
	ds_read_b128 v[178:181], v197 offset:50176
	ds_read_b128 v[182:185], v197 offset:51200
	ds_read_b128 v[186:189], v197 offset:52224
	ds_read_b128 v[198:201], v197 offset:53248
	ds_read_b128 v[202:205], v197 offset:54272
	ds_read_b128 v[206:209], v197 offset:55296
	ds_read_b128 v[210:213], v197 offset:56320
	global_load_lds_dwordx4 v[190:191], off
	s_add_i32 m0, s42, 0x2000
	s_add_u32 s40, s40, 0x100080
	v_lshl_add_u64 v[190:191], v[214:215], 0, s[8:9]
	s_addc_u32 s41, s41, 0
	s_add_i32 s42, s62, s3
	global_load_lds_dwordx4 v[190:191], off
	v_lshl_add_u64 v[190:191], s[40:41], 0, v[128:129]
	s_mov_b32 m0, s42
	s_nop 0
	global_load_lds_dwordx4 v[190:191], off
	v_lshl_add_u64 v[190:191], s[40:41], 0, v[130:131]
	s_add_i32 m0, s42, 0x2000
	s_nop 0
	global_load_lds_dwordx4 v[190:191], off
	v_lshl_add_u64 v[190:191], v[216:217], 0, s[8:9]
	s_mov_b32 m0, s44
	s_nop 0
	global_load_lds_dwordx4 v[190:191], off
	v_lshl_add_u64 v[190:191], v[218:219], 0, s[8:9]
	s_mov_b32 m0, s45
	s_nop 0
	global_load_lds_dwordx4 v[190:191], off
	s_waitcnt vmcnt(8)
	s_waitcnt lgkmcnt(0)
	s_barrier
	s_setprio 1
	s_waitcnt lgkmcnt(0)
	v_mfma_f32_16x16x32_bf16 v[60:63], v[142:145], v[174:177], v[60:63]
	v_mfma_f32_16x16x32_bf16 v[60:63], v[146:149], v[178:181], v[60:63]
	v_mfma_f32_16x16x32_bf16 v[56:59], v[150:153], v[174:177], v[56:59]
	v_mfma_f32_16x16x32_bf16 v[56:59], v[154:157], v[178:181], v[56:59]
	v_mfma_f32_16x16x32_bf16 v[40:43], v[150:153], v[182:185], v[40:43]
	v_mfma_f32_16x16x32_bf16 v[40:43], v[154:157], v[186:189], v[40:43]
	v_mfma_f32_16x16x32_bf16 v[44:47], v[142:145], v[182:185], v[44:47]
	v_mfma_f32_16x16x32_bf16 v[44:47], v[146:149], v[186:189], v[44:47]
	v_mfma_f32_16x16x32_bf16 v[28:31], v[142:145], v[198:201], v[28:31]
	v_mfma_f32_16x16x32_bf16 v[28:31], v[146:149], v[202:205], v[28:31]
	v_mfma_f32_16x16x32_bf16 v[24:27], v[150:153], v[198:201], v[24:27]
	v_mfma_f32_16x16x32_bf16 v[24:27], v[154:157], v[202:205], v[24:27]
	v_mfma_f32_16x16x32_bf16 v[8:11], v[150:153], v[206:209], v[8:11]
	v_mfma_f32_16x16x32_bf16 v[8:11], v[154:157], v[210:213], v[8:11]
	v_mfma_f32_16x16x32_bf16 v[12:15], v[142:145], v[206:209], v[12:15]
	v_mfma_f32_16x16x32_bf16 v[12:15], v[146:149], v[210:213], v[12:15]
	s_setprio 0
	s_setprio 1
	v_mfma_f32_16x16x32_bf16 v[52:55], v[158:161], v[174:177], v[52:55]
	v_mfma_f32_16x16x32_bf16 v[52:55], v[162:165], v[178:181], v[52:55]
	v_mfma_f32_16x16x32_bf16 v[48:51], v[166:169], v[174:177], v[48:51]
	v_mfma_f32_16x16x32_bf16 v[48:51], v[170:173], v[178:181], v[48:51]
	v_mfma_f32_16x16x32_bf16 v[32:35], v[166:169], v[182:185], v[32:35]
	v_mfma_f32_16x16x32_bf16 v[32:35], v[170:173], v[186:189], v[32:35]
	v_mfma_f32_16x16x32_bf16 v[36:39], v[158:161], v[182:185], v[36:39]
	v_mfma_f32_16x16x32_bf16 v[36:39], v[162:165], v[186:189], v[36:39]
	v_mfma_f32_16x16x32_bf16 v[20:23], v[158:161], v[198:201], v[20:23]
	v_mfma_f32_16x16x32_bf16 v[20:23], v[162:165], v[202:205], v[20:23]
	v_mfma_f32_16x16x32_bf16 v[16:19], v[166:169], v[198:201], v[16:19]
	v_mfma_f32_16x16x32_bf16 v[16:19], v[170:173], v[202:205], v[16:19]
	v_mfma_f32_16x16x32_bf16 v[0:3], v[166:169], v[206:209], v[0:3]
	v_mfma_f32_16x16x32_bf16 v[0:3], v[170:173], v[210:213], v[0:3]
	v_mfma_f32_16x16x32_bf16 v[4:7], v[158:161], v[206:209], v[4:7]
	v_mfma_f32_16x16x32_bf16 v[4:7], v[162:165], v[210:213], v[4:7]
	s_setprio 0
	s_barrier
	s_add_i32 s58, s58, 2
	s_add_u32 s38, s38, 0x100
	s_addc_u32 s39, s39, 0
	s_add_u32 s56, s56, 0x100
	s_addc_u32 s57, s57, 0

.LBB0_831:
	v_lshl_add_u32 v142, s36, 8, v133
	v_lshl_or_b32 v198, s53, 8, v194
	v_ashrrev_i32_e32 v199, 31, v198
	v_ashrrev_i32_e32 v143, 31, v142
	v_lshl_add_u64 v[144:145], v[198:199], 1, s[14:15]
	v_lshlrev_b64 v[146:147], 11, v[142:143]
	v_lshl_add_u64 v[148:149], v[144:145], 0, v[146:147]
	global_load_dwordx2 v[200:201], v[148:149], off
	global_load_dwordx2 v[202:203], v[148:149], off offset:32
	global_load_dwordx2 v[204:205], v[148:149], off offset:256
	global_load_dwordx2 v[206:207], v[148:149], off offset:288
	v_or_b32_e32 v150, 16, v142
	v_or_b32_e32 v152, 32, v142
	v_or_b32_e32 v154, 48, v142
	v_ashrrev_i32_e32 v151, 31, v150
	v_ashrrev_i32_e32 v153, 31, v152
	v_ashrrev_i32_e32 v155, 31, v154
	v_sub_u32_e32 v146, v142, v193
	v_lshlrev_b64 v[142:143], 11, v[150:151]
	v_lshlrev_b64 v[150:151], 11, v[152:153]
	v_lshlrev_b64 v[152:153], 11, v[154:155]
	v_add_co_u32_e32 v154, vcc, s48, v148
	v_lshl_add_u64 v[142:143], v[144:145], 0, v[142:143]
	s_nop 0
	v_addc_co_u32_e32 v155, vcc, 0, v149, vcc
	v_add_co_u32_e32 v158, vcc, s49, v148
	v_lshl_add_u64 v[150:151], v[144:145], 0, v[150:151]
	s_nop 0
	v_addc_co_u32_e32 v159, vcc, 0, v149, vcc
	v_add_co_u32_e32 v210, vcc, s50, v148
	v_lshl_add_u64 v[144:145], v[144:145], 0, v[152:153]
	s_nop 0
	v_addc_co_u32_e32 v211, vcc, 0, v149, vcc
	v_lshl_add_u64 v[152:153], v[148:149], 0, s[16:17]
	v_lshl_add_u64 v[156:157], v[148:149], 0, s[18:19]
	v_lshl_add_u64 v[208:209], v[148:149], 0, s[20:21]
	v_lshl_add_u64 v[212:213], v[148:149], 0, s[22:23]
	v_add_co_u32_e32 v148, vcc, s51, v148
	v_ashrrev_i32_e32 v147, 31, v146
	s_nop 0
	v_addc_co_u32_e32 v149, vcc, 0, v149, vcc
	global_load_dwordx2 v[214:215], v[142:143], off
	global_load_dwordx2 v[216:217], v[142:143], off offset:32
	global_load_dwordx2 v[218:219], v[142:143], off offset:256
	global_load_dwordx2 v[220:221], v[142:143], off offset:288
	global_load_dwordx2 v[190:191], v[150:151], off
	global_load_dwordx2 v[188:189], v[150:151], off offset:32
	global_load_dwordx2 v[186:187], v[150:151], off offset:256
	global_load_dwordx2 v[184:185], v[150:151], off offset:288
	global_load_dwordx2 v[182:183], v[144:145], off
	global_load_dwordx2 v[180:181], v[144:145], off offset:32
	global_load_dwordx2 v[178:179], v[144:145], off offset:256
	global_load_dwordx2 v[176:177], v[144:145], off offset:288
	global_load_dwordx2 v[174:175], v[154:155], off
	global_load_dwordx2 v[172:173], v[152:153], off offset:32
	global_load_dwordx2 v[170:171], v[152:153], off offset:256
	global_load_dwordx2 v[168:169], v[152:153], off offset:288
	global_load_dwordx2 v[166:167], v[158:159], off
	global_load_dwordx2 v[164:165], v[156:157], off offset:32
	global_load_dwordx2 v[162:163], v[156:157], off offset:256
	global_load_dwordx2 v[160:161], v[156:157], off offset:288
	s_nop 0
	global_load_dwordx2 v[158:159], v[210:211], off
	global_load_dwordx2 v[156:157], v[208:209], off offset:32
	global_load_dwordx2 v[154:155], v[208:209], off offset:256
	global_load_dwordx2 v[152:153], v[208:209], off offset:288
	global_load_dwordx2 v[150:151], v[148:149], off
	s_nop 0
	global_load_dwordx2 v[148:149], v[212:213], off offset:32
	global_load_dwordx2 v[144:145], v[212:213], off offset:256
	global_load_dwordx2 v[142:143], v[212:213], off offset:288
	v_or_b32_e32 v198, v198, v132
	s_waitcnt vmcnt(31)
	v_lshlrev_b32_e32 v208, 16, v200
	v_and_b32_e32 v209, 0xffff0000, v200
	v_lshlrev_b32_e32 v200, 16, v201
	v_and_b32_e32 v201, 0xffff0000, v201
	s_waitcnt vmcnt(30)
	v_lshlrev_b32_e32 v210, 16, v202
	v_and_b32_e32 v211, 0xffff0000, v202
	v_lshlrev_b32_e32 v202, 16, v203
	v_and_b32_e32 v203, 0xffff0000, v203
	v_pk_add_f32 v[208:209], v[124:125], v[208:209]
	v_pk_add_f32 v[124:125], v[126:127], v[200:201]
	v_pk_add_f32 v[200:201], v[122:123], v[202:203]
	v_pk_add_f32 v[126:127], v[120:121], v[210:211]
	v_cndmask_b32_e64 v120, v125, v201, s[0:1]
	v_cndmask_b32_e64 v121, v124, v200, s[0:1]
	v_cndmask_b32_e64 v122, v209, v127, s[0:1]
	v_cndmask_b32_e64 v123, v208, v126, s[0:1]
	v_mov_b32_dpp v212, v121 quad_perm:[1,0,3,2] row_mask:0xf bank_mask:0xf bound_ctrl:1
	v_mov_b32_dpp v213, v120 quad_perm:[1,0,3,2] row_mask:0xf bank_mask:0xf bound_ctrl:1
	v_lshlrev_b64 v[120:121], 12, v[146:147]
	v_mov_b32_dpp v210, v123 quad_perm:[1,0,3,2] row_mask:0xf bank_mask:0xf bound_ctrl:1
	v_mov_b32_dpp v211, v122 quad_perm:[1,0,3,2] row_mask:0xf bank_mask:0xf bound_ctrl:1
	v_lshl_add_u64 v[202:203], s[74:75], 0, v[120:121]
	v_lshlrev_b64 v[120:121], 2, v[198:199]
	v_cndmask_b32_e64 v125, v213, v125, s[0:1]
	v_cndmask_b32_e64 v124, v212, v124, s[0:1]
	v_cndmask_b32_e64 v123, v211, v209, s[0:1]
	v_cndmask_b32_e64 v122, v210, v208, s[0:1]
	v_lshl_add_u64 v[198:199], v[202:203], 0, v[120:121]
	global_store_dwordx4 v[198:199], v[122:125], off nt
	s_nop 1
	v_cndmask_b32_e64 v122, v126, v210, s[0:1]
	v_add_co_u32_e32 v126, vcc, s52, v198
	v_cndmask_b32_e64 v125, v201, v213, s[0:1]
	v_cndmask_b32_e64 v124, v200, v212, s[0:1]
	v_cndmask_b32_e64 v123, v127, v211, s[0:1]
	v_addc_co_u32_e32 v127, vcc, 0, v199, vcc
	global_store_dwordx4 v[126:127], v[122:125], off nt
	s_nop 1
	s_waitcnt vmcnt(31)
	v_lshlrev_b32_e32 v122, 16, v204
	v_and_b32_e32 v123, 0xffff0000, v204
	v_lshlrev_b32_e32 v124, 16, v205
	v_and_b32_e32 v125, 0xffff0000, v205
	v_pk_add_f32 v[116:117], v[116:117], v[122:123]
	v_pk_add_f32 v[118:119], v[118:119], v[124:125]
	s_waitcnt vmcnt(30)
	v_lshlrev_b32_e32 v122, 16, v206
	v_and_b32_e32 v123, 0xffff0000, v206
	v_lshlrev_b32_e32 v124, 16, v207
	v_and_b32_e32 v125, 0xffff0000, v207
	v_pk_add_f32 v[122:123], v[112:113], v[122:123]
	v_pk_add_f32 v[124:125], v[114:115], v[124:125]
	v_cndmask_b32_e64 v114, v117, v123, s[0:1]
	v_cndmask_b32_e64 v112, v119, v125, s[0:1]
	v_cndmask_b32_e64 v113, v118, v124, s[0:1]
	v_cndmask_b32_e64 v115, v116, v122, s[0:1]
	v_mov_b32_dpp v200, v114 quad_perm:[1,0,3,2] row_mask:0xf bank_mask:0xf bound_ctrl:1
	v_mov_b32_dpp v201, v113 quad_perm:[1,0,3,2] row_mask:0xf bank_mask:0xf bound_ctrl:1
	v_mov_b32_dpp v147, v115 quad_perm:[1,0,3,2] row_mask:0xf bank_mask:0xf bound_ctrl:1
	v_mov_b32_dpp v202, v112 quad_perm:[1,0,3,2] row_mask:0xf bank_mask:0xf bound_ctrl:1
	v_cndmask_b32_e64 v115, v202, v119, s[0:1]
	v_cndmask_b32_e64 v114, v201, v118, s[0:1]
	v_cndmask_b32_e64 v113, v200, v117, s[0:1]
	v_cndmask_b32_e64 v112, v147, v116, s[0:1]
	global_store_dwordx4 v[198:199], v[112:115], off offset:512 nt
	s_waitcnt vmcnt(30)
	v_lshlrev_b32_e32 v116, 16, v215
	v_and_b32_e32 v117, 0xffff0000, v215
	v_cndmask_b32_e64 v115, v125, v202, s[0:1]
	v_cndmask_b32_e64 v114, v124, v201, s[0:1]
	v_cndmask_b32_e64 v113, v123, v200, s[0:1]
	v_cndmask_b32_e64 v112, v122, v147, s[0:1]
	global_store_dwordx4 v[126:127], v[112:115], off offset:512 nt
	v_pk_add_f32 v[110:111], v[110:111], v[116:117]
	s_waitcnt vmcnt(30)
	v_lshlrev_b32_e32 v116, 16, v217
	v_lshlrev_b32_e32 v114, 16, v214
	v_and_b32_e32 v115, 0xffff0000, v214
	v_pk_add_f32 v[108:109], v[108:109], v[114:115]
	v_lshlrev_b32_e32 v114, 16, v216
	v_and_b32_e32 v115, 0xffff0000, v216
	v_and_b32_e32 v117, 0xffff0000, v217
	v_pk_add_f32 v[114:115], v[104:105], v[114:115]
	v_add_u32_e32 v112, 16, v146
	v_pk_add_f32 v[116:117], v[106:107], v[116:117]
	v_cndmask_b32_e64 v106, v109, v115, s[0:1]
	v_cndmask_b32_e64 v107, v108, v114, s[0:1]
	v_ashrrev_i32_e32 v113, 31, v112
	v_cndmask_b32_e64 v104, v111, v117, s[0:1]
	v_cndmask_b32_e64 v105, v110, v116, s[0:1]
	v_mov_b32_dpp v118, v107 quad_perm:[1,0,3,2] row_mask:0xf bank_mask:0xf bound_ctrl:1
	v_mov_b32_dpp v119, v106 quad_perm:[1,0,3,2] row_mask:0xf bank_mask:0xf bound_ctrl:1
	v_mov_b32_dpp v122, v105 quad_perm:[1,0,3,2] row_mask:0xf bank_mask:0xf bound_ctrl:1
	v_mov_b32_dpp v123, v104 quad_perm:[1,0,3,2] row_mask:0xf bank_mask:0xf bound_ctrl:1
	v_cndmask_b32_e64 v105, v119, v109, s[0:1]
	v_cndmask_b32_e64 v104, v118, v108, s[0:1]
	v_lshlrev_b64 v[108:109], 12, v[112:113]
	v_lshl_add_u64 v[108:109], s[74:75], 0, v[108:109]
	v_lshl_add_u64 v[108:109], v[108:109], 0, v[120:121]
	v_cndmask_b32_e64 v107, v123, v111, s[0:1]
	v_cndmask_b32_e64 v106, v122, v110, s[0:1]
	v_add_co_u32_e32 v110, vcc, s52, v108
	global_store_dwordx4 v[108:109], v[104:107], off nt
	s_nop 0
	v_addc_co_u32_e32 v111, vcc, 0, v109, vcc
	v_cndmask_b32_e64 v107, v117, v123, s[0:1]
	v_cndmask_b32_e64 v106, v116, v122, s[0:1]
	v_cndmask_b32_e64 v105, v115, v119, s[0:1]
	v_cndmask_b32_e64 v104, v114, v118, s[0:1]
	global_store_dwordx4 v[110:111], v[104:107], off nt
	s_nop 1
	s_waitcnt vmcnt(31)
	v_lshlrev_b32_e32 v104, 16, v218
	v_and_b32_e32 v105, 0xffff0000, v218
	v_lshlrev_b32_e32 v106, 16, v219
	v_and_b32_e32 v107, 0xffff0000, v219
	v_pk_add_f32 v[100:101], v[100:101], v[104:105]
	v_pk_add_f32 v[102:103], v[102:103], v[106:107]
	s_waitcnt vmcnt(30)
	v_lshlrev_b32_e32 v104, 16, v220
	v_and_b32_e32 v105, 0xffff0000, v220
	v_lshlrev_b32_e32 v106, 16, v221
	v_and_b32_e32 v107, 0xffff0000, v221
	v_pk_add_f32 v[104:105], v[96:97], v[104:105]
	v_pk_add_f32 v[106:107], v[98:99], v[106:107]
	v_cndmask_b32_e64 v98, v101, v105, s[0:1]
	v_cndmask_b32_e64 v96, v103, v107, s[0:1]
	v_cndmask_b32_e64 v97, v102, v106, s[0:1]
	v_cndmask_b32_e64 v99, v100, v104, s[0:1]
	v_mov_b32_dpp v113, v98 quad_perm:[1,0,3,2] row_mask:0xf bank_mask:0xf bound_ctrl:1
	v_mov_b32_dpp v114, v97 quad_perm:[1,0,3,2] row_mask:0xf bank_mask:0xf bound_ctrl:1
	v_mov_b32_dpp v112, v99 quad_perm:[1,0,3,2] row_mask:0xf bank_mask:0xf bound_ctrl:1
	v_mov_b32_dpp v115, v96 quad_perm:[1,0,3,2] row_mask:0xf bank_mask:0xf bound_ctrl:1
	v_cndmask_b32_e64 v99, v115, v103, s[0:1]
	v_cndmask_b32_e64 v98, v114, v102, s[0:1]
	v_cndmask_b32_e64 v97, v113, v101, s[0:1]
	v_cndmask_b32_e64 v96, v112, v100, s[0:1]
	global_store_dwordx4 v[108:109], v[96:99], off offset:512 nt
	s_waitcnt vmcnt(30)
	v_lshlrev_b32_e32 v100, 16, v191
	v_and_b32_e32 v101, 0xffff0000, v191
	v_cndmask_b32_e64 v99, v107, v115, s[0:1]
	v_cndmask_b32_e64 v98, v106, v114, s[0:1]
	v_cndmask_b32_e64 v97, v105, v113, s[0:1]
	v_cndmask_b32_e64 v96, v104, v112, s[0:1]
	global_store_dwordx4 v[110:111], v[96:99], off offset:512 nt
	v_pk_add_f32 v[94:95], v[94:95], v[100:101]
	s_waitcnt vmcnt(30)
	v_lshlrev_b32_e32 v100, 16, v189
	v_lshlrev_b32_e32 v98, 16, v190
	v_and_b32_e32 v99, 0xffff0000, v190
	v_pk_add_f32 v[92:93], v[92:93], v[98:99]
	v_lshlrev_b32_e32 v98, 16, v188
	v_and_b32_e32 v99, 0xffff0000, v188
	v_and_b32_e32 v101, 0xffff0000, v189
	v_pk_add_f32 v[98:99], v[88:89], v[98:99]
	v_add_u32_e32 v96, 32, v146
	v_pk_add_f32 v[100:101], v[90:91], v[100:101]
	v_cndmask_b32_e64 v90, v93, v99, s[0:1]
	v_cndmask_b32_e64 v91, v92, v98, s[0:1]
	v_ashrrev_i32_e32 v97, 31, v96
	v_cndmask_b32_e64 v88, v95, v101, s[0:1]
	v_cndmask_b32_e64 v89, v94, v100, s[0:1]
	v_mov_b32_dpp v102, v91 quad_perm:[1,0,3,2] row_mask:0xf bank_mask:0xf bound_ctrl:1
	v_mov_b32_dpp v103, v90 quad_perm:[1,0,3,2] row_mask:0xf bank_mask:0xf bound_ctrl:1
	v_mov_b32_dpp v104, v89 quad_perm:[1,0,3,2] row_mask:0xf bank_mask:0xf bound_ctrl:1
	v_mov_b32_dpp v105, v88 quad_perm:[1,0,3,2] row_mask:0xf bank_mask:0xf bound_ctrl:1
	v_cndmask_b32_e64 v89, v103, v93, s[0:1]
	v_cndmask_b32_e64 v88, v102, v92, s[0:1]
	v_lshlrev_b64 v[92:93], 12, v[96:97]
	v_lshl_add_u64 v[92:93], s[74:75], 0, v[92:93]
	v_lshl_add_u64 v[92:93], v[92:93], 0, v[120:121]
	v_cndmask_b32_e64 v91, v105, v95, s[0:1]
	v_cndmask_b32_e64 v90, v104, v94, s[0:1]
	v_add_co_u32_e32 v94, vcc, s52, v92
	global_store_dwordx4 v[92:93], v[88:91], off nt
	s_nop 0
	v_addc_co_u32_e32 v95, vcc, 0, v93, vcc
	v_cndmask_b32_e64 v91, v101, v105, s[0:1]
	v_cndmask_b32_e64 v90, v100, v104, s[0:1]
	v_cndmask_b32_e64 v89, v99, v103, s[0:1]
	v_cndmask_b32_e64 v88, v98, v102, s[0:1]
	global_store_dwordx4 v[94:95], v[88:91], off nt
	s_nop 1
	s_waitcnt vmcnt(31)
	v_lshlrev_b32_e32 v88, 16, v186
	v_and_b32_e32 v89, 0xffff0000, v186
	v_lshlrev_b32_e32 v90, 16, v187
	v_and_b32_e32 v91, 0xffff0000, v187
	v_pk_add_f32 v[84:85], v[84:85], v[88:89]
	v_pk_add_f32 v[86:87], v[86:87], v[90:91]
	s_waitcnt vmcnt(30)
	v_lshlrev_b32_e32 v88, 16, v184
	v_and_b32_e32 v89, 0xffff0000, v184
	v_lshlrev_b32_e32 v90, 16, v185
	v_and_b32_e32 v91, 0xffff0000, v185
	v_pk_add_f32 v[88:89], v[80:81], v[88:89]
	v_pk_add_f32 v[90:91], v[82:83], v[90:91]
	v_cndmask_b32_e64 v82, v85, v89, s[0:1]
	v_cndmask_b32_e64 v80, v87, v91, s[0:1]
	v_cndmask_b32_e64 v81, v86, v90, s[0:1]
	v_cndmask_b32_e64 v83, v84, v88, s[0:1]
	v_mov_b32_dpp v97, v82 quad_perm:[1,0,3,2] row_mask:0xf bank_mask:0xf bound_ctrl:1
	v_mov_b32_dpp v98, v81 quad_perm:[1,0,3,2] row_mask:0xf bank_mask:0xf bound_ctrl:1
	v_mov_b32_dpp v96, v83 quad_perm:[1,0,3,2] row_mask:0xf bank_mask:0xf bound_ctrl:1
	v_mov_b32_dpp v99, v80 quad_perm:[1,0,3,2] row_mask:0xf bank_mask:0xf bound_ctrl:1
	v_cndmask_b32_e64 v83, v99, v87, s[0:1]
	v_cndmask_b32_e64 v82, v98, v86, s[0:1]
	v_cndmask_b32_e64 v81, v97, v85, s[0:1]
	v_cndmask_b32_e64 v80, v96, v84, s[0:1]
	global_store_dwordx4 v[92:93], v[80:83], off offset:512 nt
	s_waitcnt vmcnt(30)
	v_lshlrev_b32_e32 v84, 16, v183
	v_and_b32_e32 v85, 0xffff0000, v183
	v_cndmask_b32_e64 v83, v91, v99, s[0:1]
	v_cndmask_b32_e64 v82, v90, v98, s[0:1]
	v_cndmask_b32_e64 v81, v89, v97, s[0:1]
	v_cndmask_b32_e64 v80, v88, v96, s[0:1]
	global_store_dwordx4 v[94:95], v[80:83], off offset:512 nt
	v_pk_add_f32 v[78:79], v[78:79], v[84:85]
	s_waitcnt vmcnt(30)
	v_lshlrev_b32_e32 v84, 16, v181
	v_lshlrev_b32_e32 v82, 16, v182
	v_and_b32_e32 v83, 0xffff0000, v182
	v_pk_add_f32 v[76:77], v[76:77], v[82:83]
	v_lshlrev_b32_e32 v82, 16, v180
	v_and_b32_e32 v83, 0xffff0000, v180
	v_and_b32_e32 v85, 0xffff0000, v181
	v_pk_add_f32 v[82:83], v[72:73], v[82:83]
	v_add_u32_e32 v80, 48, v146
	v_pk_add_f32 v[84:85], v[74:75], v[84:85]
	v_cndmask_b32_e64 v74, v77, v83, s[0:1]
	v_cndmask_b32_e64 v75, v76, v82, s[0:1]
	v_ashrrev_i32_e32 v81, 31, v80
	v_cndmask_b32_e64 v72, v79, v85, s[0:1]
	v_cndmask_b32_e64 v73, v78, v84, s[0:1]
	v_mov_b32_dpp v86, v75 quad_perm:[1,0,3,2] row_mask:0xf bank_mask:0xf bound_ctrl:1
	v_mov_b32_dpp v87, v74 quad_perm:[1,0,3,2] row_mask:0xf bank_mask:0xf bound_ctrl:1
	v_mov_b32_dpp v88, v73 quad_perm:[1,0,3,2] row_mask:0xf bank_mask:0xf bound_ctrl:1
	v_mov_b32_dpp v89, v72 quad_perm:[1,0,3,2] row_mask:0xf bank_mask:0xf bound_ctrl:1
	v_cndmask_b32_e64 v73, v87, v77, s[0:1]
	v_cndmask_b32_e64 v72, v86, v76, s[0:1]
	v_lshlrev_b64 v[76:77], 12, v[80:81]
	v_lshl_add_u64 v[76:77], s[74:75], 0, v[76:77]
	v_lshl_add_u64 v[76:77], v[76:77], 0, v[120:121]
	v_cndmask_b32_e64 v75, v89, v79, s[0:1]
	v_cndmask_b32_e64 v74, v88, v78, s[0:1]
	v_add_co_u32_e32 v78, vcc, s52, v76
	global_store_dwordx4 v[76:77], v[72:75], off nt
	s_nop 0
	v_addc_co_u32_e32 v79, vcc, 0, v77, vcc
	v_cndmask_b32_e64 v75, v85, v89, s[0:1]
	v_cndmask_b32_e64 v74, v84, v88, s[0:1]
	v_cndmask_b32_e64 v73, v83, v87, s[0:1]
	v_cndmask_b32_e64 v72, v82, v86, s[0:1]
	global_store_dwordx4 v[78:79], v[72:75], off nt
	s_nop 1
	s_waitcnt vmcnt(31)
	v_lshlrev_b32_e32 v72, 16, v178
	v_and_b32_e32 v73, 0xffff0000, v178
	v_lshlrev_b32_e32 v74, 16, v179
	v_and_b32_e32 v75, 0xffff0000, v179
	v_pk_add_f32 v[68:69], v[68:69], v[72:73]
	v_pk_add_f32 v[70:71], v[70:71], v[74:75]
	s_waitcnt vmcnt(30)
	v_lshlrev_b32_e32 v72, 16, v176
	v_and_b32_e32 v73, 0xffff0000, v176
	v_lshlrev_b32_e32 v74, 16, v177
	v_and_b32_e32 v75, 0xffff0000, v177
	v_pk_add_f32 v[72:73], v[64:65], v[72:73]
	v_pk_add_f32 v[74:75], v[66:67], v[74:75]
	v_cndmask_b32_e64 v66, v69, v73, s[0:1]
	v_cndmask_b32_e64 v64, v71, v75, s[0:1]
	v_cndmask_b32_e64 v65, v70, v74, s[0:1]
	v_cndmask_b32_e64 v67, v68, v72, s[0:1]
	v_mov_b32_dpp v81, v66 quad_perm:[1,0,3,2] row_mask:0xf bank_mask:0xf bound_ctrl:1
	v_mov_b32_dpp v82, v65 quad_perm:[1,0,3,2] row_mask:0xf bank_mask:0xf bound_ctrl:1
	v_mov_b32_dpp v80, v67 quad_perm:[1,0,3,2] row_mask:0xf bank_mask:0xf bound_ctrl:1
	v_mov_b32_dpp v83, v64 quad_perm:[1,0,3,2] row_mask:0xf bank_mask:0xf bound_ctrl:1
	v_cndmask_b32_e64 v67, v83, v71, s[0:1]
	v_cndmask_b32_e64 v66, v82, v70, s[0:1]
	v_cndmask_b32_e64 v65, v81, v69, s[0:1]
	v_cndmask_b32_e64 v64, v80, v68, s[0:1]
	global_store_dwordx4 v[76:77], v[64:67], off offset:512 nt
	s_waitcnt vmcnt(30)
	v_lshlrev_b32_e32 v68, 16, v175
	v_and_b32_e32 v69, 0xffff0000, v175
	v_cndmask_b32_e64 v67, v75, v83, s[0:1]
	v_cndmask_b32_e64 v66, v74, v82, s[0:1]
	v_cndmask_b32_e64 v65, v73, v81, s[0:1]
	v_cndmask_b32_e64 v64, v72, v80, s[0:1]
	global_store_dwordx4 v[78:79], v[64:67], off offset:512 nt
	v_pk_add_f32 v[62:63], v[62:63], v[68:69]
	s_waitcnt vmcnt(30)
	v_lshlrev_b32_e32 v68, 16, v173
	v_lshlrev_b32_e32 v66, 16, v174
	v_and_b32_e32 v67, 0xffff0000, v174
	v_pk_add_f32 v[60:61], v[60:61], v[66:67]
	v_lshlrev_b32_e32 v66, 16, v172
	v_and_b32_e32 v67, 0xffff0000, v172
	v_and_b32_e32 v69, 0xffff0000, v173
	v_pk_add_f32 v[66:67], v[56:57], v[66:67]
	v_add_u32_e32 v64, 0x80, v146
	v_pk_add_f32 v[68:69], v[58:59], v[68:69]
	v_cndmask_b32_e64 v58, v61, v67, s[0:1]
	v_cndmask_b32_e64 v59, v60, v66, s[0:1]
	v_ashrrev_i32_e32 v65, 31, v64
	v_cndmask_b32_e64 v56, v63, v69, s[0:1]
	v_cndmask_b32_e64 v57, v62, v68, s[0:1]
	v_mov_b32_dpp v70, v59 quad_perm:[1,0,3,2] row_mask:0xf bank_mask:0xf bound_ctrl:1
	v_mov_b32_dpp v71, v58 quad_perm:[1,0,3,2] row_mask:0xf bank_mask:0xf bound_ctrl:1
	v_mov_b32_dpp v72, v57 quad_perm:[1,0,3,2] row_mask:0xf bank_mask:0xf bound_ctrl:1
	v_mov_b32_dpp v73, v56 quad_perm:[1,0,3,2] row_mask:0xf bank_mask:0xf bound_ctrl:1
	v_cndmask_b32_e64 v57, v71, v61, s[0:1]
	v_cndmask_b32_e64 v56, v70, v60, s[0:1]
	v_lshlrev_b64 v[60:61], 12, v[64:65]
	v_lshl_add_u64 v[60:61], s[74:75], 0, v[60:61]
	v_lshl_add_u64 v[60:61], v[60:61], 0, v[120:121]
	v_cndmask_b32_e64 v59, v73, v63, s[0:1]
	v_cndmask_b32_e64 v58, v72, v62, s[0:1]
	v_add_co_u32_e32 v62, vcc, s52, v60
	global_store_dwordx4 v[60:61], v[56:59], off nt
	s_nop 0
	v_addc_co_u32_e32 v63, vcc, 0, v61, vcc
	v_cndmask_b32_e64 v59, v69, v73, s[0:1]
	v_cndmask_b32_e64 v58, v68, v72, s[0:1]
	v_cndmask_b32_e64 v57, v67, v71, s[0:1]
	v_cndmask_b32_e64 v56, v66, v70, s[0:1]
	global_store_dwordx4 v[62:63], v[56:59], off nt
	s_nop 1
	s_waitcnt vmcnt(31)
	v_lshlrev_b32_e32 v56, 16, v170
	v_and_b32_e32 v57, 0xffff0000, v170
	v_lshlrev_b32_e32 v58, 16, v171
	v_and_b32_e32 v59, 0xffff0000, v171
	v_pk_add_f32 v[52:53], v[52:53], v[56:57]
	v_pk_add_f32 v[54:55], v[54:55], v[58:59]
	s_waitcnt vmcnt(30)
	v_lshlrev_b32_e32 v56, 16, v168
	v_and_b32_e32 v57, 0xffff0000, v168
	v_lshlrev_b32_e32 v58, 16, v169
	v_and_b32_e32 v59, 0xffff0000, v169
	v_pk_add_f32 v[56:57], v[48:49], v[56:57]
	v_pk_add_f32 v[58:59], v[50:51], v[58:59]
	v_cndmask_b32_e64 v50, v53, v57, s[0:1]
	v_cndmask_b32_e64 v48, v55, v59, s[0:1]
	v_cndmask_b32_e64 v49, v54, v58, s[0:1]
	v_cndmask_b32_e64 v51, v52, v56, s[0:1]
	v_mov_b32_dpp v65, v50 quad_perm:[1,0,3,2] row_mask:0xf bank_mask:0xf bound_ctrl:1
	v_mov_b32_dpp v66, v49 quad_perm:[1,0,3,2] row_mask:0xf bank_mask:0xf bound_ctrl:1
	v_mov_b32_dpp v64, v51 quad_perm:[1,0,3,2] row_mask:0xf bank_mask:0xf bound_ctrl:1
	v_mov_b32_dpp v67, v48 quad_perm:[1,0,3,2] row_mask:0xf bank_mask:0xf bound_ctrl:1
	v_cndmask_b32_e64 v51, v67, v55, s[0:1]
	v_cndmask_b32_e64 v50, v66, v54, s[0:1]
	v_cndmask_b32_e64 v49, v65, v53, s[0:1]
	v_cndmask_b32_e64 v48, v64, v52, s[0:1]
	global_store_dwordx4 v[60:61], v[48:51], off offset:512 nt
	s_waitcnt vmcnt(30)
	v_lshlrev_b32_e32 v52, 16, v167
	v_and_b32_e32 v53, 0xffff0000, v167
	v_cndmask_b32_e64 v51, v59, v67, s[0:1]
	v_cndmask_b32_e64 v50, v58, v66, s[0:1]
	v_cndmask_b32_e64 v49, v57, v65, s[0:1]
	v_cndmask_b32_e64 v48, v56, v64, s[0:1]
	global_store_dwordx4 v[62:63], v[48:51], off offset:512 nt
	v_pk_add_f32 v[46:47], v[46:47], v[52:53]
	s_waitcnt vmcnt(30)
	v_lshlrev_b32_e32 v52, 16, v165
	v_lshlrev_b32_e32 v50, 16, v166
	v_and_b32_e32 v51, 0xffff0000, v166
	v_pk_add_f32 v[44:45], v[44:45], v[50:51]
	v_lshlrev_b32_e32 v50, 16, v164
	v_and_b32_e32 v51, 0xffff0000, v164
	v_and_b32_e32 v53, 0xffff0000, v165
	v_pk_add_f32 v[50:51], v[40:41], v[50:51]
	v_add_u32_e32 v48, 0x90, v146
	v_pk_add_f32 v[52:53], v[42:43], v[52:53]
	v_cndmask_b32_e64 v42, v45, v51, s[0:1]
	v_cndmask_b32_e64 v43, v44, v50, s[0:1]
	v_ashrrev_i32_e32 v49, 31, v48
	v_cndmask_b32_e64 v40, v47, v53, s[0:1]
	v_cndmask_b32_e64 v41, v46, v52, s[0:1]
	v_mov_b32_dpp v54, v43 quad_perm:[1,0,3,2] row_mask:0xf bank_mask:0xf bound_ctrl:1
	v_mov_b32_dpp v55, v42 quad_perm:[1,0,3,2] row_mask:0xf bank_mask:0xf bound_ctrl:1
	v_mov_b32_dpp v56, v41 quad_perm:[1,0,3,2] row_mask:0xf bank_mask:0xf bound_ctrl:1
	v_mov_b32_dpp v57, v40 quad_perm:[1,0,3,2] row_mask:0xf bank_mask:0xf bound_ctrl:1
	v_cndmask_b32_e64 v41, v55, v45, s[0:1]
	v_cndmask_b32_e64 v40, v54, v44, s[0:1]
	v_lshlrev_b64 v[44:45], 12, v[48:49]
	v_lshl_add_u64 v[44:45], s[74:75], 0, v[44:45]
	v_lshl_add_u64 v[44:45], v[44:45], 0, v[120:121]
	v_cndmask_b32_e64 v43, v57, v47, s[0:1]
	v_cndmask_b32_e64 v42, v56, v46, s[0:1]
	v_add_co_u32_e32 v46, vcc, s52, v44
	global_store_dwordx4 v[44:45], v[40:43], off nt
	s_nop 0
	v_addc_co_u32_e32 v47, vcc, 0, v45, vcc
	v_cndmask_b32_e64 v43, v53, v57, s[0:1]
	v_cndmask_b32_e64 v42, v52, v56, s[0:1]
	v_cndmask_b32_e64 v41, v51, v55, s[0:1]
	v_cndmask_b32_e64 v40, v50, v54, s[0:1]
	global_store_dwordx4 v[46:47], v[40:43], off nt
	s_nop 1
	s_waitcnt vmcnt(31)
	v_lshlrev_b32_e32 v40, 16, v162
	v_and_b32_e32 v41, 0xffff0000, v162
	v_lshlrev_b32_e32 v42, 16, v163
	v_and_b32_e32 v43, 0xffff0000, v163
	v_pk_add_f32 v[36:37], v[36:37], v[40:41]
	v_pk_add_f32 v[38:39], v[38:39], v[42:43]
	s_waitcnt vmcnt(30)
	v_lshlrev_b32_e32 v40, 16, v160
	v_and_b32_e32 v41, 0xffff0000, v160
	v_lshlrev_b32_e32 v42, 16, v161
	v_and_b32_e32 v43, 0xffff0000, v161
	v_pk_add_f32 v[40:41], v[32:33], v[40:41]
	v_pk_add_f32 v[42:43], v[34:35], v[42:43]
	v_cndmask_b32_e64 v34, v37, v41, s[0:1]
	v_cndmask_b32_e64 v32, v39, v43, s[0:1]
	v_cndmask_b32_e64 v33, v38, v42, s[0:1]
	v_cndmask_b32_e64 v35, v36, v40, s[0:1]
	v_mov_b32_dpp v49, v34 quad_perm:[1,0,3,2] row_mask:0xf bank_mask:0xf bound_ctrl:1
	v_mov_b32_dpp v50, v33 quad_perm:[1,0,3,2] row_mask:0xf bank_mask:0xf bound_ctrl:1
	v_mov_b32_dpp v48, v35 quad_perm:[1,0,3,2] row_mask:0xf bank_mask:0xf bound_ctrl:1
	v_mov_b32_dpp v51, v32 quad_perm:[1,0,3,2] row_mask:0xf bank_mask:0xf bound_ctrl:1
	v_cndmask_b32_e64 v35, v51, v39, s[0:1]
	v_cndmask_b32_e64 v34, v50, v38, s[0:1]
	v_cndmask_b32_e64 v33, v49, v37, s[0:1]
	v_cndmask_b32_e64 v32, v48, v36, s[0:1]
	global_store_dwordx4 v[44:45], v[32:35], off offset:512 nt
	s_waitcnt vmcnt(30)
	v_lshlrev_b32_e32 v36, 16, v159
	v_and_b32_e32 v37, 0xffff0000, v159
	v_cndmask_b32_e64 v35, v43, v51, s[0:1]
	v_cndmask_b32_e64 v34, v42, v50, s[0:1]
	v_cndmask_b32_e64 v33, v41, v49, s[0:1]
	v_cndmask_b32_e64 v32, v40, v48, s[0:1]
	global_store_dwordx4 v[46:47], v[32:35], off offset:512 nt
	v_pk_add_f32 v[30:31], v[30:31], v[36:37]
	s_waitcnt vmcnt(30)
	v_lshlrev_b32_e32 v36, 16, v157
	v_lshlrev_b32_e32 v34, 16, v158
	v_and_b32_e32 v35, 0xffff0000, v158
	v_pk_add_f32 v[28:29], v[28:29], v[34:35]
	v_lshlrev_b32_e32 v34, 16, v156
	v_and_b32_e32 v35, 0xffff0000, v156
	v_and_b32_e32 v37, 0xffff0000, v157
	v_pk_add_f32 v[34:35], v[24:25], v[34:35]
	v_add_u32_e32 v32, 0xa0, v146
	v_pk_add_f32 v[36:37], v[26:27], v[36:37]
	v_cndmask_b32_e64 v26, v29, v35, s[0:1]
	v_cndmask_b32_e64 v27, v28, v34, s[0:1]
	v_ashrrev_i32_e32 v33, 31, v32
	v_cndmask_b32_e64 v24, v31, v37, s[0:1]
	v_cndmask_b32_e64 v25, v30, v36, s[0:1]
	v_mov_b32_dpp v38, v27 quad_perm:[1,0,3,2] row_mask:0xf bank_mask:0xf bound_ctrl:1
	v_mov_b32_dpp v39, v26 quad_perm:[1,0,3,2] row_mask:0xf bank_mask:0xf bound_ctrl:1
	v_mov_b32_dpp v40, v25 quad_perm:[1,0,3,2] row_mask:0xf bank_mask:0xf bound_ctrl:1
	v_mov_b32_dpp v41, v24 quad_perm:[1,0,3,2] row_mask:0xf bank_mask:0xf bound_ctrl:1
	v_cndmask_b32_e64 v25, v39, v29, s[0:1]
	v_cndmask_b32_e64 v24, v38, v28, s[0:1]
	v_lshlrev_b64 v[28:29], 12, v[32:33]
	v_lshl_add_u64 v[28:29], s[74:75], 0, v[28:29]
	v_lshl_add_u64 v[28:29], v[28:29], 0, v[120:121]
	v_cndmask_b32_e64 v27, v41, v31, s[0:1]
	v_cndmask_b32_e64 v26, v40, v30, s[0:1]
	v_add_co_u32_e32 v30, vcc, s52, v28
	global_store_dwordx4 v[28:29], v[24:27], off nt
	s_nop 0
	v_addc_co_u32_e32 v31, vcc, 0, v29, vcc
	v_cndmask_b32_e64 v27, v37, v41, s[0:1]
	v_cndmask_b32_e64 v26, v36, v40, s[0:1]
	v_cndmask_b32_e64 v25, v35, v39, s[0:1]
	v_cndmask_b32_e64 v24, v34, v38, s[0:1]
	global_store_dwordx4 v[30:31], v[24:27], off nt
	s_nop 1
	s_waitcnt vmcnt(31)
	v_lshlrev_b32_e32 v24, 16, v154
	v_and_b32_e32 v25, 0xffff0000, v154
	v_lshlrev_b32_e32 v26, 16, v155
	v_and_b32_e32 v27, 0xffff0000, v155
	v_pk_add_f32 v[20:21], v[20:21], v[24:25]
	v_pk_add_f32 v[22:23], v[22:23], v[26:27]
	s_waitcnt vmcnt(30)
	v_lshlrev_b32_e32 v24, 16, v152
	v_and_b32_e32 v25, 0xffff0000, v152
	v_lshlrev_b32_e32 v26, 16, v153
	v_and_b32_e32 v27, 0xffff0000, v153
	v_pk_add_f32 v[24:25], v[16:17], v[24:25]
	v_pk_add_f32 v[26:27], v[18:19], v[26:27]
	v_cndmask_b32_e64 v18, v21, v25, s[0:1]
	v_cndmask_b32_e64 v16, v23, v27, s[0:1]
	v_cndmask_b32_e64 v17, v22, v26, s[0:1]
	v_cndmask_b32_e64 v19, v20, v24, s[0:1]
	v_mov_b32_dpp v33, v18 quad_perm:[1,0,3,2] row_mask:0xf bank_mask:0xf bound_ctrl:1
	v_mov_b32_dpp v34, v17 quad_perm:[1,0,3,2] row_mask:0xf bank_mask:0xf bound_ctrl:1
	v_mov_b32_dpp v32, v19 quad_perm:[1,0,3,2] row_mask:0xf bank_mask:0xf bound_ctrl:1
	v_mov_b32_dpp v35, v16 quad_perm:[1,0,3,2] row_mask:0xf bank_mask:0xf bound_ctrl:1
	v_cndmask_b32_e64 v19, v35, v23, s[0:1]
	v_cndmask_b32_e64 v18, v34, v22, s[0:1]
	v_cndmask_b32_e64 v17, v33, v21, s[0:1]
	v_cndmask_b32_e64 v16, v32, v20, s[0:1]
	global_store_dwordx4 v[28:29], v[16:19], off offset:512 nt
	s_waitcnt vmcnt(30)
	v_lshlrev_b32_e32 v20, 16, v151
	v_and_b32_e32 v21, 0xffff0000, v151
	v_cndmask_b32_e64 v19, v27, v35, s[0:1]
	v_cndmask_b32_e64 v18, v26, v34, s[0:1]
	v_cndmask_b32_e64 v17, v25, v33, s[0:1]
	v_cndmask_b32_e64 v16, v24, v32, s[0:1]
	global_store_dwordx4 v[30:31], v[16:19], off offset:512 nt
	v_pk_add_f32 v[14:15], v[14:15], v[20:21]
	s_waitcnt vmcnt(30)
	v_lshlrev_b32_e32 v20, 16, v149
	v_lshlrev_b32_e32 v18, 16, v150
	v_and_b32_e32 v19, 0xffff0000, v150
	v_pk_add_f32 v[12:13], v[12:13], v[18:19]
	v_lshlrev_b32_e32 v18, 16, v148
	v_and_b32_e32 v19, 0xffff0000, v148
	v_and_b32_e32 v21, 0xffff0000, v149
	v_pk_add_f32 v[18:19], v[8:9], v[18:19]
	v_add_u32_e32 v16, 0xb0, v146
	v_pk_add_f32 v[20:21], v[10:11], v[20:21]
	v_cndmask_b32_e64 v10, v13, v19, s[0:1]
	v_cndmask_b32_e64 v11, v12, v18, s[0:1]
	v_ashrrev_i32_e32 v17, 31, v16
	v_cndmask_b32_e64 v8, v15, v21, s[0:1]
	v_cndmask_b32_e64 v9, v14, v20, s[0:1]
	v_mov_b32_dpp v22, v11 quad_perm:[1,0,3,2] row_mask:0xf bank_mask:0xf bound_ctrl:1
	v_mov_b32_dpp v23, v10 quad_perm:[1,0,3,2] row_mask:0xf bank_mask:0xf bound_ctrl:1
	v_mov_b32_dpp v24, v9 quad_perm:[1,0,3,2] row_mask:0xf bank_mask:0xf bound_ctrl:1
	v_mov_b32_dpp v25, v8 quad_perm:[1,0,3,2] row_mask:0xf bank_mask:0xf bound_ctrl:1
	v_cndmask_b32_e64 v9, v23, v13, s[0:1]
	v_cndmask_b32_e64 v8, v22, v12, s[0:1]
	v_lshlrev_b64 v[12:13], 12, v[16:17]
	v_lshl_add_u64 v[12:13], s[74:75], 0, v[12:13]
	v_lshl_add_u64 v[12:13], v[12:13], 0, v[120:121]
	v_cndmask_b32_e64 v11, v25, v15, s[0:1]
	v_cndmask_b32_e64 v10, v24, v14, s[0:1]
	v_add_co_u32_e32 v14, vcc, s52, v12
	global_store_dwordx4 v[12:13], v[8:11], off nt
	s_nop 0
	v_addc_co_u32_e32 v15, vcc, 0, v13, vcc
	v_cndmask_b32_e64 v11, v21, v25, s[0:1]
	v_cndmask_b32_e64 v10, v20, v24, s[0:1]
	v_cndmask_b32_e64 v9, v19, v23, s[0:1]
	v_cndmask_b32_e64 v8, v18, v22, s[0:1]
	global_store_dwordx4 v[14:15], v[8:11], off nt
	s_andn2_b64 vcc, exec, s[4:5]
	s_mov_b64 s[4:5], -1
	s_waitcnt vmcnt(31)
	v_lshlrev_b32_e32 v8, 16, v144
	v_and_b32_e32 v9, 0xffff0000, v144
	v_lshlrev_b32_e32 v10, 16, v145
	v_and_b32_e32 v11, 0xffff0000, v145
	v_pk_add_f32 v[4:5], v[4:5], v[8:9]
	v_pk_add_f32 v[6:7], v[6:7], v[10:11]
	s_waitcnt vmcnt(30)
	v_lshlrev_b32_e32 v8, 16, v142
	v_and_b32_e32 v9, 0xffff0000, v142
	v_lshlrev_b32_e32 v10, 16, v143
	v_and_b32_e32 v11, 0xffff0000, v143
	v_pk_add_f32 v[8:9], v[0:1], v[8:9]
	v_pk_add_f32 v[10:11], v[2:3], v[10:11]
	v_cndmask_b32_e64 v2, v5, v9, s[0:1]
	v_cndmask_b32_e64 v0, v7, v11, s[0:1]
	v_cndmask_b32_e64 v1, v6, v10, s[0:1]
	v_cndmask_b32_e64 v3, v4, v8, s[0:1]
	v_mov_b32_dpp v17, v2 quad_perm:[1,0,3,2] row_mask:0xf bank_mask:0xf bound_ctrl:1
	v_mov_b32_dpp v18, v1 quad_perm:[1,0,3,2] row_mask:0xf bank_mask:0xf bound_ctrl:1
	v_mov_b32_dpp v16, v3 quad_perm:[1,0,3,2] row_mask:0xf bank_mask:0xf bound_ctrl:1
	v_mov_b32_dpp v19, v0 quad_perm:[1,0,3,2] row_mask:0xf bank_mask:0xf bound_ctrl:1
	v_cndmask_b32_e64 v3, v19, v7, s[0:1]
	v_cndmask_b32_e64 v2, v18, v6, s[0:1]
	v_cndmask_b32_e64 v1, v17, v5, s[0:1]
	v_cndmask_b32_e64 v0, v16, v4, s[0:1]
	global_store_dwordx4 v[12:13], v[0:3], off offset:512 nt
	s_nop 1
	v_cndmask_b32_e64 v3, v11, v19, s[0:1]
	v_cndmask_b32_e64 v2, v10, v18, s[0:1]
	v_cndmask_b32_e64 v1, v9, v17, s[0:1]
	v_cndmask_b32_e64 v0, v8, v16, s[0:1]
	global_store_dwordx4 v[14:15], v[0:3], off offset:512 nt
	s_mov_b32 s98, 1
	s_cbranch_vccnz .LBB0_820
	s_andn2_b64 vcc, exec, s[6:7]
	s_cbranch_vccnz .LBB0_819
	s_barrier
	s_branch .LBB0_819
